# all K-loop load-section trims combined, no alignment padding: scalar-base LDS-DMA (loops + peeled iterations), stage bases in ds_read offsets, m0 wait states filled by ds_reads, no 64-bit VALU in any
# speedup vs baseline: 1.0019x; 1.0019x over previous
.LBB0_287:
	s_ashr_i32 s21, s20, 31
	s_lshl_b64 s[22:23], s[20:21], 19
	s_add_u32 s22, s80, s22
	s_addc_u32 s23, s81, s23
	s_and_b64 s[24:25], s[6:7], exec
	s_cselect_b32 s21, s23, s29
	s_cselect_b32 s36, s22, s28
	s_ashr_i32 s19, s18, 31
	s_lshl_b64 s[24:25], s[18:19], 19
	s_add_u32 s24, s40, s24
	s_addc_u32 s25, s41, s25
	s_and_b64 s[34:35], s[6:7], exec
	s_cselect_b32 s19, s25, s31
	s_cselect_b32 s37, s24, s30
	s_add_u32 s38, s30, 0x100
	s_addc_u32 s39, s31, 0
	s_add_u32 s28, s28, 0x40080
	s_addc_u32 s29, s29, 0
	s_mov_b32 s55, -2
	s_add_u32 s30, s28, 0xfffc0080
	s_addc_u32 s31, s29, -1
	s_add_i32 s56, 0, 0x10000
	s_cmp_eq_u32 s55, 12
	s_cselect_b32 s35, s21, s31
	s_cselect_b32 s34, s36, s30
	s_cselect_b32 s31, s19, s39
	s_cselect_b32 s30, s37, s38
	s_add_i32 s58, 0, 0x14000
	ds_read_b128 v[142:145], v147
	ds_read_b128 v[158:161], v147 offset:1024
	ds_read_b128 v[162:165], v147 offset:2048
	ds_read_b128 v[166:169], v147 offset:3072
	ds_read_b128 v[170:173], v147 offset:16384
	ds_read_b128 v[174:177], v147 offset:17408
	ds_read_b128 v[178:181], v147 offset:18432
	ds_read_b128 v[182:185], v147 offset:19456
	s_add_i32 m0, s44, 0xc000
	ds_read_b128 v[186:189], v157
	ds_read_b128 v[190:193], v157 offset:1024
	ds_read_b128 v[194:197], v157 offset:2048
	ds_read_b128 v[198:201], v157 offset:3072
	ds_read_b128 v[202:205], v157 offset:4096
	ds_read_b128 v[206:209], v157 offset:5120
	ds_read_b128 v[220:223], v157 offset:6144
	ds_read_b128 v[236:239], v157 offset:7168
	global_load_lds_dwordx4 v140, s[28:29]
	s_add_i32 m0, s44, 0xe000
	s_nop 0
	global_load_lds_dwordx4 v138, s[28:29]
	s_waitcnt vmcnt(8)
	s_waitcnt lgkmcnt(0)
	s_barrier
	v_mfma_f32_16x16x32_bf16 v[126:129], v[142:145], v[186:189], 0
	v_mfma_f32_16x16x32_bf16 v[122:125], v[162:165], v[186:189], 0
	v_mfma_f32_16x16x32_bf16 v[110:113], v[142:145], v[194:197], 0
	v_mfma_f32_16x16x32_bf16 v[106:109], v[162:165], v[194:197], 0
	v_mfma_f32_16x16x32_bf16 v[94:97], v[142:145], v[202:205], 0
	v_mfma_f32_16x16x32_bf16 v[90:93], v[162:165], v[202:205], 0
	v_mfma_f32_16x16x32_bf16 v[78:81], v[142:145], v[220:223], 0
	v_mfma_f32_16x16x32_bf16 v[74:77], v[162:165], v[220:223], 0
	v_mfma_f32_16x16x32_bf16 v[126:129], v[158:161], v[190:193], v[126:129]
	v_mfma_f32_16x16x32_bf16 v[122:125], v[166:169], v[190:193], v[122:125]
	v_mfma_f32_16x16x32_bf16 v[110:113], v[158:161], v[198:201], v[110:113]
	v_mfma_f32_16x16x32_bf16 v[106:109], v[166:169], v[198:201], v[106:109]
	v_mfma_f32_16x16x32_bf16 v[94:97], v[158:161], v[206:209], v[94:97]
	v_mfma_f32_16x16x32_bf16 v[90:93], v[166:169], v[206:209], v[90:93]
	v_mfma_f32_16x16x32_bf16 v[78:81], v[158:161], v[236:239], v[78:81]
	v_mfma_f32_16x16x32_bf16 v[74:77], v[166:169], v[236:239], v[74:77]
	v_mfma_f32_16x16x32_bf16 v[118:121], v[170:173], v[186:189], 0
	v_mfma_f32_16x16x32_bf16 v[114:117], v[178:181], v[186:189], 0
	v_mfma_f32_16x16x32_bf16 v[102:105], v[170:173], v[194:197], 0
	v_mfma_f32_16x16x32_bf16 v[98:101], v[178:181], v[194:197], 0
	v_mfma_f32_16x16x32_bf16 v[86:89], v[170:173], v[202:205], 0
	v_mfma_f32_16x16x32_bf16 v[82:85], v[178:181], v[202:205], 0
	v_mfma_f32_16x16x32_bf16 v[70:73], v[170:173], v[220:223], 0
	v_mfma_f32_16x16x32_bf16 v[66:69], v[178:181], v[220:223], 0
	v_mfma_f32_16x16x32_bf16 v[118:121], v[174:177], v[190:193], v[118:121]
	v_mfma_f32_16x16x32_bf16 v[114:117], v[182:185], v[190:193], v[114:117]
	v_mfma_f32_16x16x32_bf16 v[102:105], v[174:177], v[198:201], v[102:105]
	v_mfma_f32_16x16x32_bf16 v[98:101], v[182:185], v[198:201], v[98:101]
	v_mfma_f32_16x16x32_bf16 v[86:89], v[174:177], v[206:209], v[86:89]
	v_mfma_f32_16x16x32_bf16 v[82:85], v[182:185], v[206:209], v[82:85]
	v_mfma_f32_16x16x32_bf16 v[70:73], v[174:177], v[236:239], v[70:73]
	v_mfma_f32_16x16x32_bf16 v[66:69], v[182:185], v[236:239], v[66:69]
	s_barrier
	s_add_i32 s56, s56, s27
	s_mov_b32 m0, s56
	ds_read_b128 v[186:189], v157 offset:16384
	ds_read_b128 v[190:193], v157 offset:17408
	ds_read_b128 v[194:197], v157 offset:18432
	ds_read_b128 v[198:201], v157 offset:19456
	ds_read_b128 v[202:205], v157 offset:20480
	ds_read_b128 v[206:209], v157 offset:21504
	ds_read_b128 v[220:223], v157 offset:22528
	ds_read_b128 v[236:239], v157 offset:23552
	global_load_lds_dwordx4 v132, s[30:31]
	s_add_i32 m0, s56, 0x2000
	s_add_u32 s56, s30, 0x40000
	s_addc_u32 s57, s31, 0
	s_add_i32 s58, s58, s27
	global_load_lds_dwordx4 v136, s[30:31]
	s_mov_b32 m0, s58
	s_nop 0
	global_load_lds_dwordx4 v132, s[56:57]
	s_add_i32 m0, s58, 0x2000
	s_nop 0
	global_load_lds_dwordx4 v136, s[56:57]
	s_mov_b32 m0, s44
	s_nop 0
	global_load_lds_dwordx4 v130, s[34:35]
	s_mov_b32 m0, s45
	s_nop 0
	global_load_lds_dwordx4 v134, s[34:35]
	s_waitcnt vmcnt(8)
	s_waitcnt lgkmcnt(0)
	s_barrier
	v_mfma_f32_16x16x32_bf16 v[62:65], v[142:145], v[186:189], 0
	v_mfma_f32_16x16x32_bf16 v[58:61], v[162:165], v[186:189], 0
	v_mfma_f32_16x16x32_bf16 v[46:49], v[142:145], v[194:197], 0
	v_mfma_f32_16x16x32_bf16 v[42:45], v[162:165], v[194:197], 0
	v_mfma_f32_16x16x32_bf16 v[30:33], v[142:145], v[202:205], 0
	v_mfma_f32_16x16x32_bf16 v[26:29], v[162:165], v[202:205], 0
	v_mfma_f32_16x16x32_bf16 v[14:17], v[142:145], v[220:223], 0
	v_mfma_f32_16x16x32_bf16 v[10:13], v[162:165], v[220:223], 0
	v_mfma_f32_16x16x32_bf16 v[62:65], v[158:161], v[190:193], v[62:65]
	v_mfma_f32_16x16x32_bf16 v[58:61], v[166:169], v[190:193], v[58:61]
	v_mfma_f32_16x16x32_bf16 v[46:49], v[158:161], v[198:201], v[46:49]
	v_mfma_f32_16x16x32_bf16 v[42:45], v[166:169], v[198:201], v[42:45]
	v_mfma_f32_16x16x32_bf16 v[30:33], v[158:161], v[206:209], v[30:33]
	v_mfma_f32_16x16x32_bf16 v[26:29], v[166:169], v[206:209], v[26:29]
	v_mfma_f32_16x16x32_bf16 v[14:17], v[158:161], v[236:239], v[14:17]
	v_mfma_f32_16x16x32_bf16 v[10:13], v[166:169], v[236:239], v[10:13]
	v_mfma_f32_16x16x32_bf16 v[54:57], v[170:173], v[186:189], 0
	v_mfma_f32_16x16x32_bf16 v[50:53], v[178:181], v[186:189], 0
	v_mfma_f32_16x16x32_bf16 v[38:41], v[170:173], v[194:197], 0
	v_mfma_f32_16x16x32_bf16 v[34:37], v[178:181], v[194:197], 0
	v_mfma_f32_16x16x32_bf16 v[22:25], v[170:173], v[202:205], 0
	v_mfma_f32_16x16x32_bf16 v[18:21], v[178:181], v[202:205], 0
	v_mfma_f32_16x16x32_bf16 v[6:9], v[170:173], v[220:223], 0
	v_mfma_f32_16x16x32_bf16 v[2:5], v[178:181], v[220:223], 0
	v_mfma_f32_16x16x32_bf16 v[54:57], v[174:177], v[190:193], v[54:57]
	v_mfma_f32_16x16x32_bf16 v[50:53], v[182:185], v[190:193], v[50:53]
	v_mfma_f32_16x16x32_bf16 v[38:41], v[174:177], v[198:201], v[38:41]
	v_mfma_f32_16x16x32_bf16 v[34:37], v[182:185], v[198:201], v[34:37]
	v_mfma_f32_16x16x32_bf16 v[22:25], v[174:177], v[206:209], v[22:25]
	v_mfma_f32_16x16x32_bf16 v[18:21], v[182:185], v[206:209], v[18:21]
	v_mfma_f32_16x16x32_bf16 v[6:9], v[174:177], v[236:239], v[6:9]
	v_mfma_f32_16x16x32_bf16 v[2:5], v[182:185], v[236:239], v[2:5]
	s_barrier
	s_add_i32 s56, 0, 0x18000
	s_add_i32 s57, 0, 0x1c000
	ds_read_b128 v[142:145], v147 offset:32768
	ds_read_b128 v[158:161], v147 offset:33792
	ds_read_b128 v[162:165], v147 offset:34816
	ds_read_b128 v[166:169], v147 offset:35840
	ds_read_b128 v[170:173], v147 offset:49152
	ds_read_b128 v[174:177], v147 offset:50176
	ds_read_b128 v[178:181], v147 offset:51200
	ds_read_b128 v[182:185], v147 offset:52224
	s_add_u32 s34, s34, 0x40000
	s_addc_u32 s35, s35, 0
	s_mov_b32 m0, s43
	ds_read_b128 v[186:189], v157 offset:32768
	ds_read_b128 v[190:193], v157 offset:33792
	ds_read_b128 v[194:197], v157 offset:34816
	ds_read_b128 v[198:201], v157 offset:35840
	ds_read_b128 v[202:205], v157 offset:36864
	ds_read_b128 v[206:209], v157 offset:37888
	ds_read_b128 v[220:223], v157 offset:38912
	ds_read_b128 v[236:239], v157 offset:39936
	global_load_lds_dwordx4 v130, s[34:35]
	s_mov_b32 m0, s46
	s_nop 0
	global_load_lds_dwordx4 v134, s[34:35]
	s_waitcnt vmcnt(8)
	s_waitcnt lgkmcnt(0)
	s_barrier
	v_mfma_f32_16x16x32_bf16 v[126:129], v[142:145], v[186:189], v[126:129]
	v_mfma_f32_16x16x32_bf16 v[122:125], v[162:165], v[186:189], v[122:125]
	v_mfma_f32_16x16x32_bf16 v[110:113], v[142:145], v[194:197], v[110:113]
	v_mfma_f32_16x16x32_bf16 v[106:109], v[162:165], v[194:197], v[106:109]
	v_mfma_f32_16x16x32_bf16 v[94:97], v[142:145], v[202:205], v[94:97]
	v_mfma_f32_16x16x32_bf16 v[90:93], v[162:165], v[202:205], v[90:93]
	v_mfma_f32_16x16x32_bf16 v[78:81], v[142:145], v[220:223], v[78:81]
	v_mfma_f32_16x16x32_bf16 v[74:77], v[162:165], v[220:223], v[74:77]
	v_mfma_f32_16x16x32_bf16 v[126:129], v[158:161], v[190:193], v[126:129]
	v_mfma_f32_16x16x32_bf16 v[122:125], v[166:169], v[190:193], v[122:125]
	v_mfma_f32_16x16x32_bf16 v[110:113], v[158:161], v[198:201], v[110:113]
	v_mfma_f32_16x16x32_bf16 v[106:109], v[166:169], v[198:201], v[106:109]
	v_mfma_f32_16x16x32_bf16 v[94:97], v[158:161], v[206:209], v[94:97]
	v_mfma_f32_16x16x32_bf16 v[90:93], v[166:169], v[206:209], v[90:93]
	v_mfma_f32_16x16x32_bf16 v[78:81], v[158:161], v[236:239], v[78:81]
	v_mfma_f32_16x16x32_bf16 v[74:77], v[166:169], v[236:239], v[74:77]
	v_mfma_f32_16x16x32_bf16 v[118:121], v[170:173], v[186:189], v[118:121]
	v_mfma_f32_16x16x32_bf16 v[114:117], v[178:181], v[186:189], v[114:117]
	v_mfma_f32_16x16x32_bf16 v[102:105], v[170:173], v[194:197], v[102:105]
	v_mfma_f32_16x16x32_bf16 v[98:101], v[178:181], v[194:197], v[98:101]
	v_mfma_f32_16x16x32_bf16 v[86:89], v[170:173], v[202:205], v[86:89]
	v_mfma_f32_16x16x32_bf16 v[82:85], v[178:181], v[202:205], v[82:85]
	v_mfma_f32_16x16x32_bf16 v[70:73], v[170:173], v[220:223], v[70:73]
	v_mfma_f32_16x16x32_bf16 v[66:69], v[178:181], v[220:223], v[66:69]
	v_mfma_f32_16x16x32_bf16 v[118:121], v[174:177], v[190:193], v[118:121]
	v_mfma_f32_16x16x32_bf16 v[114:117], v[182:185], v[190:193], v[114:117]
	v_mfma_f32_16x16x32_bf16 v[102:105], v[174:177], v[198:201], v[102:105]
	v_mfma_f32_16x16x32_bf16 v[98:101], v[182:185], v[198:201], v[98:101]
	v_mfma_f32_16x16x32_bf16 v[86:89], v[174:177], v[206:209], v[86:89]
	v_mfma_f32_16x16x32_bf16 v[82:85], v[182:185], v[206:209], v[82:85]
	v_mfma_f32_16x16x32_bf16 v[70:73], v[174:177], v[236:239], v[70:73]
	v_mfma_f32_16x16x32_bf16 v[66:69], v[182:185], v[236:239], v[66:69]
	s_barrier
	s_add_u32 s100, s34, 0xfffc0080
	s_addc_u32 s101, s35, -1
	s_add_u32 s30, s30, 0x80
	s_addc_u32 s31, s31, 0
	s_add_i32 s34, s56, s27
	s_mov_b32 m0, s34
	ds_read_b128 v[186:189], v157 offset:49152
	ds_read_b128 v[190:193], v157 offset:50176
	ds_read_b128 v[194:197], v157 offset:51200
	ds_read_b128 v[198:201], v157 offset:52224
	ds_read_b128 v[202:205], v157 offset:53248
	ds_read_b128 v[206:209], v157 offset:54272
	ds_read_b128 v[220:223], v157 offset:55296
	ds_read_b128 v[236:239], v157 offset:56320
	global_load_lds_dwordx4 v132, s[30:31]
	s_add_i32 m0, s34, 0x2000
	s_add_i32 s34, s57, s27
	global_load_lds_dwordx4 v136, s[30:31]
	s_add_u32 s30, s30, 0x40000
	s_addc_u32 s31, s31, 0
	s_mov_b32 m0, s34
	s_nop 0
	global_load_lds_dwordx4 v132, s[30:31]
	s_add_i32 m0, s34, 0x2000
	s_nop 0
	global_load_lds_dwordx4 v136, s[30:31]
	s_mov_b32 m0, s47
	s_nop 0
	global_load_lds_dwordx4 v130, s[100:101]
	s_mov_b32 m0, s48
	s_nop 0
	global_load_lds_dwordx4 v134, s[100:101]
	s_waitcnt vmcnt(8)
	s_waitcnt lgkmcnt(0)
	s_barrier
	v_mfma_f32_16x16x32_bf16 v[62:65], v[142:145], v[186:189], v[62:65]
	v_mfma_f32_16x16x32_bf16 v[58:61], v[162:165], v[186:189], v[58:61]
	v_mfma_f32_16x16x32_bf16 v[46:49], v[142:145], v[194:197], v[46:49]
	v_mfma_f32_16x16x32_bf16 v[42:45], v[162:165], v[194:197], v[42:45]
	v_mfma_f32_16x16x32_bf16 v[30:33], v[142:145], v[202:205], v[30:33]
	v_mfma_f32_16x16x32_bf16 v[26:29], v[162:165], v[202:205], v[26:29]
	v_mfma_f32_16x16x32_bf16 v[14:17], v[142:145], v[220:223], v[14:17]
	v_mfma_f32_16x16x32_bf16 v[10:13], v[162:165], v[220:223], v[10:13]
	v_mfma_f32_16x16x32_bf16 v[62:65], v[158:161], v[190:193], v[62:65]
	v_mfma_f32_16x16x32_bf16 v[58:61], v[166:169], v[190:193], v[58:61]
	v_mfma_f32_16x16x32_bf16 v[46:49], v[158:161], v[198:201], v[46:49]
	v_mfma_f32_16x16x32_bf16 v[42:45], v[166:169], v[198:201], v[42:45]
	v_mfma_f32_16x16x32_bf16 v[30:33], v[158:161], v[206:209], v[30:33]
	v_mfma_f32_16x16x32_bf16 v[26:29], v[166:169], v[206:209], v[26:29]
	v_mfma_f32_16x16x32_bf16 v[14:17], v[158:161], v[236:239], v[14:17]
	v_mfma_f32_16x16x32_bf16 v[10:13], v[166:169], v[236:239], v[10:13]
	v_mfma_f32_16x16x32_bf16 v[54:57], v[170:173], v[186:189], v[54:57]
	v_mfma_f32_16x16x32_bf16 v[50:53], v[178:181], v[186:189], v[50:53]
	v_mfma_f32_16x16x32_bf16 v[38:41], v[170:173], v[194:197], v[38:41]
	v_mfma_f32_16x16x32_bf16 v[34:37], v[178:181], v[194:197], v[34:37]
	v_mfma_f32_16x16x32_bf16 v[22:25], v[170:173], v[202:205], v[22:25]
	v_mfma_f32_16x16x32_bf16 v[18:21], v[178:181], v[202:205], v[18:21]
	v_mfma_f32_16x16x32_bf16 v[6:9], v[170:173], v[220:223], v[6:9]
	v_mfma_f32_16x16x32_bf16 v[2:5], v[178:181], v[220:223], v[2:5]
	v_mfma_f32_16x16x32_bf16 v[54:57], v[174:177], v[190:193], v[54:57]
	v_mfma_f32_16x16x32_bf16 v[50:53], v[182:185], v[190:193], v[50:53]
	v_mfma_f32_16x16x32_bf16 v[38:41], v[174:177], v[198:201], v[38:41]
	v_mfma_f32_16x16x32_bf16 v[34:37], v[182:185], v[198:201], v[34:37]
	v_mfma_f32_16x16x32_bf16 v[22:25], v[174:177], v[206:209], v[22:25]
	v_mfma_f32_16x16x32_bf16 v[18:21], v[182:185], v[206:209], v[18:21]
	v_mfma_f32_16x16x32_bf16 v[6:9], v[174:177], v[236:239], v[6:9]
	v_mfma_f32_16x16x32_bf16 v[2:5], v[182:185], v[236:239], v[2:5]
	s_barrier
	s_add_i32 s55, s55, 2
	s_add_u32 s38, s38, 0x100
	s_addc_u32 s39, s39, 0
	s_add_u32 s28, s28, 0x100
	s_addc_u32 s29, s29, 0
	s_cmp_gt_u32 s55, 13
.LBB0_288:
	s_add_u32 s30, s28, 0xfffc0080
	s_addc_u32 s31, s29, -1
	s_add_i32 s56, 0, 0x10000
	s_cmp_eq_u32 s55, 12
	s_cselect_b32 s35, s21, s31
	s_cselect_b32 s34, s36, s30
	s_cselect_b32 s31, s19, s39
	s_cselect_b32 s30, s37, s38
	s_add_i32 s58, 0, 0x14000
	ds_read_b128 v[142:145], v147
	ds_read_b128 v[158:161], v147 offset:1024
	ds_read_b128 v[162:165], v147 offset:2048
	ds_read_b128 v[166:169], v147 offset:3072
	ds_read_b128 v[170:173], v147 offset:16384
	ds_read_b128 v[174:177], v147 offset:17408
	ds_read_b128 v[178:181], v147 offset:18432
	ds_read_b128 v[182:185], v147 offset:19456
	s_add_i32 m0, s44, 0xc000
	ds_read_b128 v[186:189], v157
	ds_read_b128 v[190:193], v157 offset:1024
	ds_read_b128 v[194:197], v157 offset:2048
	ds_read_b128 v[198:201], v157 offset:3072
	ds_read_b128 v[202:205], v157 offset:4096
	ds_read_b128 v[206:209], v157 offset:5120
	ds_read_b128 v[220:223], v157 offset:6144
	global_load_lds_dwordx4 v140, s[28:29]
	s_add_i32 m0, s44, 0xe000
	ds_read_b128 v[236:239], v157 offset:7168
	global_load_lds_dwordx4 v138, s[28:29]
	s_waitcnt vmcnt(8)
	s_waitcnt lgkmcnt(0)
	s_barrier
	v_mfma_f32_16x16x32_bf16 v[126:129], v[142:145], v[186:189], v[126:129]
	v_mfma_f32_16x16x32_bf16 v[122:125], v[162:165], v[186:189], v[122:125]
	v_mfma_f32_16x16x32_bf16 v[110:113], v[142:145], v[194:197], v[110:113]
	v_mfma_f32_16x16x32_bf16 v[106:109], v[162:165], v[194:197], v[106:109]
	v_mfma_f32_16x16x32_bf16 v[94:97], v[142:145], v[202:205], v[94:97]
	v_mfma_f32_16x16x32_bf16 v[90:93], v[162:165], v[202:205], v[90:93]
	v_mfma_f32_16x16x32_bf16 v[78:81], v[142:145], v[220:223], v[78:81]
	v_mfma_f32_16x16x32_bf16 v[74:77], v[162:165], v[220:223], v[74:77]
	v_mfma_f32_16x16x32_bf16 v[126:129], v[158:161], v[190:193], v[126:129]
	v_mfma_f32_16x16x32_bf16 v[122:125], v[166:169], v[190:193], v[122:125]
	v_mfma_f32_16x16x32_bf16 v[110:113], v[158:161], v[198:201], v[110:113]
	v_mfma_f32_16x16x32_bf16 v[106:109], v[166:169], v[198:201], v[106:109]
	v_mfma_f32_16x16x32_bf16 v[94:97], v[158:161], v[206:209], v[94:97]
	v_mfma_f32_16x16x32_bf16 v[90:93], v[166:169], v[206:209], v[90:93]
	v_mfma_f32_16x16x32_bf16 v[78:81], v[158:161], v[236:239], v[78:81]
	v_mfma_f32_16x16x32_bf16 v[74:77], v[166:169], v[236:239], v[74:77]
	v_mfma_f32_16x16x32_bf16 v[118:121], v[170:173], v[186:189], v[118:121]
	v_mfma_f32_16x16x32_bf16 v[114:117], v[178:181], v[186:189], v[114:117]
	v_mfma_f32_16x16x32_bf16 v[102:105], v[170:173], v[194:197], v[102:105]
	v_mfma_f32_16x16x32_bf16 v[98:101], v[178:181], v[194:197], v[98:101]
	v_mfma_f32_16x16x32_bf16 v[86:89], v[170:173], v[202:205], v[86:89]
	v_mfma_f32_16x16x32_bf16 v[82:85], v[178:181], v[202:205], v[82:85]
	v_mfma_f32_16x16x32_bf16 v[70:73], v[170:173], v[220:223], v[70:73]
	v_mfma_f32_16x16x32_bf16 v[66:69], v[178:181], v[220:223], v[66:69]
	v_mfma_f32_16x16x32_bf16 v[118:121], v[174:177], v[190:193], v[118:121]
	v_mfma_f32_16x16x32_bf16 v[114:117], v[182:185], v[190:193], v[114:117]
	v_mfma_f32_16x16x32_bf16 v[102:105], v[174:177], v[198:201], v[102:105]
	v_mfma_f32_16x16x32_bf16 v[98:101], v[182:185], v[198:201], v[98:101]
	v_mfma_f32_16x16x32_bf16 v[86:89], v[174:177], v[206:209], v[86:89]
	v_mfma_f32_16x16x32_bf16 v[82:85], v[182:185], v[206:209], v[82:85]
	v_mfma_f32_16x16x32_bf16 v[70:73], v[174:177], v[236:239], v[70:73]
	v_mfma_f32_16x16x32_bf16 v[66:69], v[182:185], v[236:239], v[66:69]
	s_barrier
	s_add_i32 s56, s56, s27
	s_mov_b32 m0, s56
	ds_read_b128 v[186:189], v157 offset:16384
	ds_read_b128 v[190:193], v157 offset:17408
	ds_read_b128 v[194:197], v157 offset:18432
	ds_read_b128 v[198:201], v157 offset:19456
	global_load_lds_dwordx4 v132, s[30:31]
	s_add_i32 m0, s56, 0x2000
	s_add_u32 s56, s30, 0x40000
	s_addc_u32 s57, s31, 0
	s_add_i32 s58, s58, s27
	global_load_lds_dwordx4 v136, s[30:31]
	s_mov_b32 m0, s58
	ds_read_b128 v[202:205], v157 offset:20480
	global_load_lds_dwordx4 v132, s[56:57]
	s_add_i32 m0, s58, 0x2000
	ds_read_b128 v[206:209], v157 offset:21504
	global_load_lds_dwordx4 v136, s[56:57]
	s_mov_b32 m0, s44
	ds_read_b128 v[220:223], v157 offset:22528
	global_load_lds_dwordx4 v130, s[34:35]
	s_mov_b32 m0, s45
	ds_read_b128 v[236:239], v157 offset:23552
	global_load_lds_dwordx4 v134, s[34:35]
	s_waitcnt vmcnt(8)
	s_waitcnt lgkmcnt(0)
	s_barrier
	v_mfma_f32_16x16x32_bf16 v[62:65], v[142:145], v[186:189], v[62:65]
	v_mfma_f32_16x16x32_bf16 v[58:61], v[162:165], v[186:189], v[58:61]
	v_mfma_f32_16x16x32_bf16 v[46:49], v[142:145], v[194:197], v[46:49]
	v_mfma_f32_16x16x32_bf16 v[42:45], v[162:165], v[194:197], v[42:45]
	v_mfma_f32_16x16x32_bf16 v[30:33], v[142:145], v[202:205], v[30:33]
	v_mfma_f32_16x16x32_bf16 v[26:29], v[162:165], v[202:205], v[26:29]
	v_mfma_f32_16x16x32_bf16 v[14:17], v[142:145], v[220:223], v[14:17]
	v_mfma_f32_16x16x32_bf16 v[10:13], v[162:165], v[220:223], v[10:13]
	v_mfma_f32_16x16x32_bf16 v[62:65], v[158:161], v[190:193], v[62:65]
	v_mfma_f32_16x16x32_bf16 v[58:61], v[166:169], v[190:193], v[58:61]
	v_mfma_f32_16x16x32_bf16 v[46:49], v[158:161], v[198:201], v[46:49]
	v_mfma_f32_16x16x32_bf16 v[42:45], v[166:169], v[198:201], v[42:45]
	v_mfma_f32_16x16x32_bf16 v[30:33], v[158:161], v[206:209], v[30:33]
	v_mfma_f32_16x16x32_bf16 v[26:29], v[166:169], v[206:209], v[26:29]
	v_mfma_f32_16x16x32_bf16 v[14:17], v[158:161], v[236:239], v[14:17]
	v_mfma_f32_16x16x32_bf16 v[10:13], v[166:169], v[236:239], v[10:13]
	v_mfma_f32_16x16x32_bf16 v[54:57], v[170:173], v[186:189], v[54:57]
	v_mfma_f32_16x16x32_bf16 v[50:53], v[178:181], v[186:189], v[50:53]
	v_mfma_f32_16x16x32_bf16 v[38:41], v[170:173], v[194:197], v[38:41]
	v_mfma_f32_16x16x32_bf16 v[34:37], v[178:181], v[194:197], v[34:37]
	v_mfma_f32_16x16x32_bf16 v[22:25], v[170:173], v[202:205], v[22:25]
	v_mfma_f32_16x16x32_bf16 v[18:21], v[178:181], v[202:205], v[18:21]
	v_mfma_f32_16x16x32_bf16 v[6:9], v[170:173], v[220:223], v[6:9]
	v_mfma_f32_16x16x32_bf16 v[2:5], v[178:181], v[220:223], v[2:5]
	v_mfma_f32_16x16x32_bf16 v[54:57], v[174:177], v[190:193], v[54:57]
	v_mfma_f32_16x16x32_bf16 v[50:53], v[182:185], v[190:193], v[50:53]
	v_mfma_f32_16x16x32_bf16 v[38:41], v[174:177], v[198:201], v[38:41]
	v_mfma_f32_16x16x32_bf16 v[34:37], v[182:185], v[198:201], v[34:37]
	v_mfma_f32_16x16x32_bf16 v[22:25], v[174:177], v[206:209], v[22:25]
	v_mfma_f32_16x16x32_bf16 v[18:21], v[182:185], v[206:209], v[18:21]
	v_mfma_f32_16x16x32_bf16 v[6:9], v[174:177], v[236:239], v[6:9]
	v_mfma_f32_16x16x32_bf16 v[2:5], v[182:185], v[236:239], v[2:5]
	s_barrier
	s_add_i32 s56, 0, 0x18000
	s_add_i32 s57, 0, 0x1c000
	ds_read_b128 v[142:145], v147 offset:32768
	ds_read_b128 v[158:161], v147 offset:33792
	ds_read_b128 v[162:165], v147 offset:34816
	ds_read_b128 v[166:169], v147 offset:35840
	ds_read_b128 v[170:173], v147 offset:49152
	ds_read_b128 v[174:177], v147 offset:50176
	ds_read_b128 v[178:181], v147 offset:51200
	ds_read_b128 v[182:185], v147 offset:52224
	s_add_u32 s34, s34, 0x40000
	s_addc_u32 s35, s35, 0
	s_mov_b32 m0, s43
	ds_read_b128 v[186:189], v157 offset:32768
	ds_read_b128 v[190:193], v157 offset:33792
	ds_read_b128 v[194:197], v157 offset:34816
	ds_read_b128 v[198:201], v157 offset:35840
	ds_read_b128 v[202:205], v157 offset:36864
	ds_read_b128 v[206:209], v157 offset:37888
	ds_read_b128 v[220:223], v157 offset:38912
	global_load_lds_dwordx4 v130, s[34:35]
	s_mov_b32 m0, s46
	ds_read_b128 v[236:239], v157 offset:39936
	global_load_lds_dwordx4 v134, s[34:35]
	s_waitcnt vmcnt(8)
	s_waitcnt lgkmcnt(0)
	s_barrier
	v_mfma_f32_16x16x32_bf16 v[126:129], v[142:145], v[186:189], v[126:129]
	v_mfma_f32_16x16x32_bf16 v[122:125], v[162:165], v[186:189], v[122:125]
	v_mfma_f32_16x16x32_bf16 v[110:113], v[142:145], v[194:197], v[110:113]
	v_mfma_f32_16x16x32_bf16 v[106:109], v[162:165], v[194:197], v[106:109]
	v_mfma_f32_16x16x32_bf16 v[94:97], v[142:145], v[202:205], v[94:97]
	v_mfma_f32_16x16x32_bf16 v[90:93], v[162:165], v[202:205], v[90:93]
	v_mfma_f32_16x16x32_bf16 v[78:81], v[142:145], v[220:223], v[78:81]
	v_mfma_f32_16x16x32_bf16 v[74:77], v[162:165], v[220:223], v[74:77]
	v_mfma_f32_16x16x32_bf16 v[126:129], v[158:161], v[190:193], v[126:129]
	v_mfma_f32_16x16x32_bf16 v[122:125], v[166:169], v[190:193], v[122:125]
	v_mfma_f32_16x16x32_bf16 v[110:113], v[158:161], v[198:201], v[110:113]
	v_mfma_f32_16x16x32_bf16 v[106:109], v[166:169], v[198:201], v[106:109]
	v_mfma_f32_16x16x32_bf16 v[94:97], v[158:161], v[206:209], v[94:97]
	v_mfma_f32_16x16x32_bf16 v[90:93], v[166:169], v[206:209], v[90:93]
	v_mfma_f32_16x16x32_bf16 v[78:81], v[158:161], v[236:239], v[78:81]
	v_mfma_f32_16x16x32_bf16 v[74:77], v[166:169], v[236:239], v[74:77]
	v_mfma_f32_16x16x32_bf16 v[118:121], v[170:173], v[186:189], v[118:121]
	v_mfma_f32_16x16x32_bf16 v[114:117], v[178:181], v[186:189], v[114:117]
	v_mfma_f32_16x16x32_bf16 v[102:105], v[170:173], v[194:197], v[102:105]
	v_mfma_f32_16x16x32_bf16 v[98:101], v[178:181], v[194:197], v[98:101]
	v_mfma_f32_16x16x32_bf16 v[86:89], v[170:173], v[202:205], v[86:89]
	v_mfma_f32_16x16x32_bf16 v[82:85], v[178:181], v[202:205], v[82:85]
	v_mfma_f32_16x16x32_bf16 v[70:73], v[170:173], v[220:223], v[70:73]
	v_mfma_f32_16x16x32_bf16 v[66:69], v[178:181], v[220:223], v[66:69]
	v_mfma_f32_16x16x32_bf16 v[118:121], v[174:177], v[190:193], v[118:121]
	v_mfma_f32_16x16x32_bf16 v[114:117], v[182:185], v[190:193], v[114:117]
	v_mfma_f32_16x16x32_bf16 v[102:105], v[174:177], v[198:201], v[102:105]
	v_mfma_f32_16x16x32_bf16 v[98:101], v[182:185], v[198:201], v[98:101]
	v_mfma_f32_16x16x32_bf16 v[86:89], v[174:177], v[206:209], v[86:89]
	v_mfma_f32_16x16x32_bf16 v[82:85], v[182:185], v[206:209], v[82:85]
	v_mfma_f32_16x16x32_bf16 v[70:73], v[174:177], v[236:239], v[70:73]
	v_mfma_f32_16x16x32_bf16 v[66:69], v[182:185], v[236:239], v[66:69]
	s_barrier
	s_add_u32 s100, s34, 0xfffc0080
	s_addc_u32 s101, s35, -1
	s_add_u32 s30, s30, 0x80
	s_addc_u32 s31, s31, 0
	s_add_i32 s34, s56, s27
	s_mov_b32 m0, s34
	ds_read_b128 v[186:189], v157 offset:49152
	ds_read_b128 v[190:193], v157 offset:50176
	ds_read_b128 v[194:197], v157 offset:51200
	ds_read_b128 v[198:201], v157 offset:52224
	global_load_lds_dwordx4 v132, s[30:31]
	s_add_i32 m0, s34, 0x2000
	s_add_i32 s34, s57, s27
	global_load_lds_dwordx4 v136, s[30:31]
	s_add_u32 s30, s30, 0x40000
	s_addc_u32 s31, s31, 0
	s_mov_b32 m0, s34
	ds_read_b128 v[202:205], v157 offset:53248
	global_load_lds_dwordx4 v132, s[30:31]
	s_add_i32 m0, s34, 0x2000
	ds_read_b128 v[206:209], v157 offset:54272
	global_load_lds_dwordx4 v136, s[30:31]
	s_mov_b32 m0, s47
	ds_read_b128 v[220:223], v157 offset:55296
	global_load_lds_dwordx4 v130, s[100:101]
	s_mov_b32 m0, s48
	ds_read_b128 v[236:239], v157 offset:56320
	global_load_lds_dwordx4 v134, s[100:101]
	s_waitcnt vmcnt(8)
	s_waitcnt lgkmcnt(0)
	s_barrier
	v_mfma_f32_16x16x32_bf16 v[62:65], v[142:145], v[186:189], v[62:65]
	v_mfma_f32_16x16x32_bf16 v[58:61], v[162:165], v[186:189], v[58:61]
	v_mfma_f32_16x16x32_bf16 v[46:49], v[142:145], v[194:197], v[46:49]
	v_mfma_f32_16x16x32_bf16 v[42:45], v[162:165], v[194:197], v[42:45]
	v_mfma_f32_16x16x32_bf16 v[30:33], v[142:145], v[202:205], v[30:33]
	v_mfma_f32_16x16x32_bf16 v[26:29], v[162:165], v[202:205], v[26:29]
	v_mfma_f32_16x16x32_bf16 v[14:17], v[142:145], v[220:223], v[14:17]
	v_mfma_f32_16x16x32_bf16 v[10:13], v[162:165], v[220:223], v[10:13]
	v_mfma_f32_16x16x32_bf16 v[62:65], v[158:161], v[190:193], v[62:65]
	v_mfma_f32_16x16x32_bf16 v[58:61], v[166:169], v[190:193], v[58:61]
	v_mfma_f32_16x16x32_bf16 v[46:49], v[158:161], v[198:201], v[46:49]
	v_mfma_f32_16x16x32_bf16 v[42:45], v[166:169], v[198:201], v[42:45]
	v_mfma_f32_16x16x32_bf16 v[30:33], v[158:161], v[206:209], v[30:33]
	v_mfma_f32_16x16x32_bf16 v[26:29], v[166:169], v[206:209], v[26:29]
	v_mfma_f32_16x16x32_bf16 v[14:17], v[158:161], v[236:239], v[14:17]
	v_mfma_f32_16x16x32_bf16 v[10:13], v[166:169], v[236:239], v[10:13]
	v_mfma_f32_16x16x32_bf16 v[54:57], v[170:173], v[186:189], v[54:57]
	v_mfma_f32_16x16x32_bf16 v[50:53], v[178:181], v[186:189], v[50:53]
	v_mfma_f32_16x16x32_bf16 v[38:41], v[170:173], v[194:197], v[38:41]
	v_mfma_f32_16x16x32_bf16 v[34:37], v[178:181], v[194:197], v[34:37]
	v_mfma_f32_16x16x32_bf16 v[22:25], v[170:173], v[202:205], v[22:25]
	v_mfma_f32_16x16x32_bf16 v[18:21], v[178:181], v[202:205], v[18:21]
	v_mfma_f32_16x16x32_bf16 v[6:9], v[170:173], v[220:223], v[6:9]
	v_mfma_f32_16x16x32_bf16 v[2:5], v[178:181], v[220:223], v[2:5]
	v_mfma_f32_16x16x32_bf16 v[54:57], v[174:177], v[190:193], v[54:57]
	v_mfma_f32_16x16x32_bf16 v[50:53], v[182:185], v[190:193], v[50:53]
	v_mfma_f32_16x16x32_bf16 v[38:41], v[174:177], v[198:201], v[38:41]
	v_mfma_f32_16x16x32_bf16 v[34:37], v[182:185], v[198:201], v[34:37]
	v_mfma_f32_16x16x32_bf16 v[22:25], v[174:177], v[206:209], v[22:25]
	v_mfma_f32_16x16x32_bf16 v[18:21], v[182:185], v[206:209], v[18:21]
	v_mfma_f32_16x16x32_bf16 v[6:9], v[174:177], v[236:239], v[6:9]
	v_mfma_f32_16x16x32_bf16 v[2:5], v[182:185], v[236:239], v[2:5]
	s_barrier
	s_add_i32 s55, s55, 2
	s_add_u32 s38, s38, 0x100
	s_addc_u32 s39, s39, 0
	s_add_u32 s28, s28, 0x100
	s_addc_u32 s29, s29, 0
	s_cmp_gt_u32 s55, 13
	s_cbranch_scc0 .LBB0_288
	s_and_b64 vcc, exec, s[12:13]
	s_cbranch_vccz .LBB0_291
	s_barrier

.LBB0_362:
	s_ashr_i32 s23, s22, 31
	s_lshl_b64 s[24:25], s[22:23], 19
	s_add_u32 s24, s80, s24
	s_addc_u32 s25, s81, s25
	s_and_b64 s[26:27], s[6:7], exec
	s_cselect_b32 s23, s25, s35
	s_cselect_b32 s39, s24, s34
	s_ashr_i32 s21, s20, 31
	s_lshl_b64 s[26:27], s[20:21], 19
	s_add_u32 s26, s45, s26
	s_addc_u32 s27, s46, s27
	s_and_b64 s[36:37], s[6:7], exec
	s_cselect_b32 s21, s27, s31
	s_cselect_b32 s40, s26, s30
	s_add_u32 s41, s30, 0x100
	s_addc_u32 s43, s31, 0
	s_add_u32 s30, s34, 0x40080
	s_addc_u32 s31, s35, 0
	s_mov_b32 s56, -2
	s_add_u32 s34, s30, 0xfffc0080
	s_addc_u32 s35, s31, -1
	s_add_i32 s57, 0, 0x10000
	s_cmp_eq_u32 s56, 12
	s_cselect_b32 s37, s23, s35
	s_cselect_b32 s36, s39, s34
	s_cselect_b32 s35, s21, s43
	s_cselect_b32 s34, s40, s41
	s_add_i32 s60, 0, 0x14000
	ds_read_b128 v[142:145], v155
	ds_read_b128 v[168:171], v155 offset:1024
	ds_read_b128 v[172:175], v155 offset:2048
	ds_read_b128 v[176:179], v155 offset:3072
	ds_read_b128 v[180:183], v155 offset:16384
	ds_read_b128 v[184:187], v155 offset:17408
	ds_read_b128 v[188:191], v155 offset:18432
	ds_read_b128 v[192:195], v155 offset:19456
	s_add_i32 m0, s48, 0xc000
	ds_read_b128 v[196:199], v157
	ds_read_b128 v[200:203], v157 offset:1024
	ds_read_b128 v[204:207], v157 offset:2048
	ds_read_b128 v[220:223], v157 offset:3072
	ds_read_b128 v[236:239], v157 offset:4096
	ds_read_b128 v[240:243], v157 offset:5120
	ds_read_b128 v[244:247], v157 offset:6144
	ds_read_b128 v[248:251], v157 offset:7168
	global_load_lds_dwordx4 v140, s[30:31]
	s_add_i32 m0, s48, 0xe000
	s_nop 0
	global_load_lds_dwordx4 v138, s[30:31]
	s_waitcnt vmcnt(8)
	s_waitcnt lgkmcnt(0)
	s_barrier
	v_mfma_f32_16x16x32_bf16 v[126:129], v[142:145], v[196:199], 0
	v_mfma_f32_16x16x32_bf16 v[118:121], v[172:175], v[196:199], 0
	v_mfma_f32_16x16x32_bf16 v[110:113], v[142:145], v[204:207], 0
	v_mfma_f32_16x16x32_bf16 v[102:105], v[172:175], v[204:207], 0
	v_mfma_f32_16x16x32_bf16 v[94:97], v[142:145], v[236:239], 0
	v_mfma_f32_16x16x32_bf16 v[86:89], v[172:175], v[236:239], 0
	v_mfma_f32_16x16x32_bf16 v[78:81], v[142:145], v[244:247], 0
	v_mfma_f32_16x16x32_bf16 v[70:73], v[172:175], v[244:247], 0
	v_mfma_f32_16x16x32_bf16 v[126:129], v[168:171], v[200:203], v[126:129]
	v_mfma_f32_16x16x32_bf16 v[118:121], v[176:179], v[200:203], v[118:121]
	v_mfma_f32_16x16x32_bf16 v[110:113], v[168:171], v[220:223], v[110:113]
	v_mfma_f32_16x16x32_bf16 v[102:105], v[176:179], v[220:223], v[102:105]
	v_mfma_f32_16x16x32_bf16 v[94:97], v[168:171], v[240:243], v[94:97]
	v_mfma_f32_16x16x32_bf16 v[86:89], v[176:179], v[240:243], v[86:89]
	v_mfma_f32_16x16x32_bf16 v[78:81], v[168:171], v[248:251], v[78:81]
	v_mfma_f32_16x16x32_bf16 v[70:73], v[176:179], v[248:251], v[70:73]
	v_mfma_f32_16x16x32_bf16 v[122:125], v[180:183], v[196:199], 0
	v_mfma_f32_16x16x32_bf16 v[114:117], v[188:191], v[196:199], 0
	v_mfma_f32_16x16x32_bf16 v[106:109], v[180:183], v[204:207], 0
	v_mfma_f32_16x16x32_bf16 v[98:101], v[188:191], v[204:207], 0
	v_mfma_f32_16x16x32_bf16 v[90:93], v[180:183], v[236:239], 0
	v_mfma_f32_16x16x32_bf16 v[82:85], v[188:191], v[236:239], 0
	v_mfma_f32_16x16x32_bf16 v[74:77], v[180:183], v[244:247], 0
	v_mfma_f32_16x16x32_bf16 v[66:69], v[188:191], v[244:247], 0
	v_mfma_f32_16x16x32_bf16 v[122:125], v[184:187], v[200:203], v[122:125]
	v_mfma_f32_16x16x32_bf16 v[114:117], v[192:195], v[200:203], v[114:117]
	v_mfma_f32_16x16x32_bf16 v[106:109], v[184:187], v[220:223], v[106:109]
	v_mfma_f32_16x16x32_bf16 v[98:101], v[192:195], v[220:223], v[98:101]
	v_mfma_f32_16x16x32_bf16 v[90:93], v[184:187], v[240:243], v[90:93]
	v_mfma_f32_16x16x32_bf16 v[82:85], v[192:195], v[240:243], v[82:85]
	v_mfma_f32_16x16x32_bf16 v[74:77], v[184:187], v[248:251], v[74:77]
	v_mfma_f32_16x16x32_bf16 v[66:69], v[192:195], v[248:251], v[66:69]
	s_barrier
	s_add_i32 s57, s57, s44
	v_lshl_add_u64 v[146:147], s[34:35], 0, v[134:135]
	s_mov_b32 m0, s57
	ds_read_b128 v[196:199], v157 offset:16384
	ds_read_b128 v[200:203], v157 offset:17408
	ds_read_b128 v[204:207], v157 offset:18432
	ds_read_b128 v[220:223], v157 offset:19456
	ds_read_b128 v[236:239], v157 offset:20480
	ds_read_b128 v[240:243], v157 offset:21504
	ds_read_b128 v[244:247], v157 offset:22528
	ds_read_b128 v[248:251], v157 offset:23552
	global_load_lds_dwordx4 v[146:147], off
	s_add_i32 m0, s57, 0x2000
	s_add_u32 s58, s34, 0x40000
	v_lshl_add_u64 v[208:209], s[34:35], 0, v[130:131]
	s_addc_u32 s59, s35, 0
	s_add_i32 s57, s60, s44
	global_load_lds_dwordx4 v[208:209], off
	s_mov_b32 m0, s57
	v_lshl_add_u64 v[230:231], s[36:37], 0, v[132:133]
	global_load_lds_dwordx4 v134, s[58:59]
	s_add_i32 m0, s57, 0x2000
	s_nop 0
	global_load_lds_dwordx4 v130, s[58:59]
	s_mov_b32 m0, s48
	v_lshl_add_u64 v[224:225], s[36:37], 0, v[136:137]
	global_load_lds_dwordx4 v[224:225], off
	s_mov_b32 m0, s49
	s_nop 0
	global_load_lds_dwordx4 v[230:231], off
	s_waitcnt vmcnt(8)
	s_waitcnt lgkmcnt(0)
	s_barrier
	v_mfma_f32_16x16x32_bf16 v[62:65], v[142:145], v[196:199], 0
	v_mfma_f32_16x16x32_bf16 v[54:57], v[172:175], v[196:199], 0
	v_mfma_f32_16x16x32_bf16 v[46:49], v[142:145], v[204:207], 0
	v_mfma_f32_16x16x32_bf16 v[38:41], v[172:175], v[204:207], 0
	v_mfma_f32_16x16x32_bf16 v[30:33], v[142:145], v[236:239], 0
	v_mfma_f32_16x16x32_bf16 v[22:25], v[172:175], v[236:239], 0
	v_mfma_f32_16x16x32_bf16 v[14:17], v[142:145], v[244:247], 0
	v_mfma_f32_16x16x32_bf16 v[6:9], v[172:175], v[244:247], 0
	v_mfma_f32_16x16x32_bf16 v[62:65], v[168:171], v[200:203], v[62:65]
	v_mfma_f32_16x16x32_bf16 v[54:57], v[176:179], v[200:203], v[54:57]
	v_mfma_f32_16x16x32_bf16 v[46:49], v[168:171], v[220:223], v[46:49]
	v_mfma_f32_16x16x32_bf16 v[38:41], v[176:179], v[220:223], v[38:41]
	v_mfma_f32_16x16x32_bf16 v[30:33], v[168:171], v[240:243], v[30:33]
	v_mfma_f32_16x16x32_bf16 v[22:25], v[176:179], v[240:243], v[22:25]
	v_mfma_f32_16x16x32_bf16 v[14:17], v[168:171], v[248:251], v[14:17]
	v_mfma_f32_16x16x32_bf16 v[6:9], v[176:179], v[248:251], v[6:9]
	v_mfma_f32_16x16x32_bf16 v[58:61], v[180:183], v[196:199], 0
	v_mfma_f32_16x16x32_bf16 v[50:53], v[188:191], v[196:199], 0
	v_mfma_f32_16x16x32_bf16 v[42:45], v[180:183], v[204:207], 0
	v_mfma_f32_16x16x32_bf16 v[34:37], v[188:191], v[204:207], 0
	v_mfma_f32_16x16x32_bf16 v[26:29], v[180:183], v[236:239], 0
	v_mfma_f32_16x16x32_bf16 v[18:21], v[188:191], v[236:239], 0
	v_mfma_f32_16x16x32_bf16 v[10:13], v[180:183], v[244:247], 0
	v_mfma_f32_16x16x32_bf16 v[2:5], v[188:191], v[244:247], 0
	v_mfma_f32_16x16x32_bf16 v[58:61], v[184:187], v[200:203], v[58:61]
	v_mfma_f32_16x16x32_bf16 v[50:53], v[192:195], v[200:203], v[50:53]
	v_mfma_f32_16x16x32_bf16 v[42:45], v[184:187], v[220:223], v[42:45]
	v_mfma_f32_16x16x32_bf16 v[34:37], v[192:195], v[220:223], v[34:37]
	v_mfma_f32_16x16x32_bf16 v[26:29], v[184:187], v[240:243], v[26:29]
	v_mfma_f32_16x16x32_bf16 v[18:21], v[192:195], v[240:243], v[18:21]
	v_mfma_f32_16x16x32_bf16 v[10:13], v[184:187], v[248:251], v[10:13]
	v_mfma_f32_16x16x32_bf16 v[2:5], v[192:195], v[248:251], v[2:5]
	s_barrier
	s_add_i32 s57, 0, 0x18000
	s_add_i32 s58, 0, 0x1c000
	ds_read_b128 v[142:145], v155 offset:32768
	ds_read_b128 v[168:171], v155 offset:33792
	ds_read_b128 v[172:175], v155 offset:34816
	ds_read_b128 v[176:179], v155 offset:35840
	ds_read_b128 v[180:183], v155 offset:49152
	ds_read_b128 v[184:187], v155 offset:50176
	ds_read_b128 v[188:191], v155 offset:51200
	ds_read_b128 v[192:195], v155 offset:52224
	s_add_u32 s36, s36, 0x40000
	s_addc_u32 s37, s37, 0
	s_mov_b32 m0, s50
	ds_read_b128 v[196:199], v157 offset:32768
	ds_read_b128 v[200:203], v157 offset:33792
	ds_read_b128 v[204:207], v157 offset:34816
	ds_read_b128 v[220:223], v157 offset:35840
	ds_read_b128 v[236:239], v157 offset:36864
	ds_read_b128 v[240:243], v157 offset:37888
	ds_read_b128 v[244:247], v157 offset:38912
	ds_read_b128 v[248:251], v157 offset:39936
	global_load_lds_dwordx4 v136, s[36:37]
	s_mov_b32 m0, s51
	s_nop 0
	global_load_lds_dwordx4 v132, s[36:37]
	s_waitcnt vmcnt(8)
	s_waitcnt lgkmcnt(0)
	s_barrier
	v_mfma_f32_16x16x32_bf16 v[126:129], v[142:145], v[196:199], v[126:129]
	v_mfma_f32_16x16x32_bf16 v[118:121], v[172:175], v[196:199], v[118:121]
	v_mfma_f32_16x16x32_bf16 v[110:113], v[142:145], v[204:207], v[110:113]
	v_mfma_f32_16x16x32_bf16 v[102:105], v[172:175], v[204:207], v[102:105]
	v_mfma_f32_16x16x32_bf16 v[94:97], v[142:145], v[236:239], v[94:97]
	v_mfma_f32_16x16x32_bf16 v[86:89], v[172:175], v[236:239], v[86:89]
	v_mfma_f32_16x16x32_bf16 v[78:81], v[142:145], v[244:247], v[78:81]
	v_mfma_f32_16x16x32_bf16 v[70:73], v[172:175], v[244:247], v[70:73]
	v_mfma_f32_16x16x32_bf16 v[126:129], v[168:171], v[200:203], v[126:129]
	v_mfma_f32_16x16x32_bf16 v[118:121], v[176:179], v[200:203], v[118:121]
	v_mfma_f32_16x16x32_bf16 v[110:113], v[168:171], v[220:223], v[110:113]
	v_mfma_f32_16x16x32_bf16 v[102:105], v[176:179], v[220:223], v[102:105]
	v_mfma_f32_16x16x32_bf16 v[94:97], v[168:171], v[240:243], v[94:97]
	v_mfma_f32_16x16x32_bf16 v[86:89], v[176:179], v[240:243], v[86:89]
	v_mfma_f32_16x16x32_bf16 v[78:81], v[168:171], v[248:251], v[78:81]
	v_mfma_f32_16x16x32_bf16 v[70:73], v[176:179], v[248:251], v[70:73]
	v_mfma_f32_16x16x32_bf16 v[122:125], v[180:183], v[196:199], v[122:125]
	v_mfma_f32_16x16x32_bf16 v[114:117], v[188:191], v[196:199], v[114:117]
	v_mfma_f32_16x16x32_bf16 v[106:109], v[180:183], v[204:207], v[106:109]
	v_mfma_f32_16x16x32_bf16 v[98:101], v[188:191], v[204:207], v[98:101]
	v_mfma_f32_16x16x32_bf16 v[90:93], v[180:183], v[236:239], v[90:93]
	v_mfma_f32_16x16x32_bf16 v[82:85], v[188:191], v[236:239], v[82:85]
	v_mfma_f32_16x16x32_bf16 v[74:77], v[180:183], v[244:247], v[74:77]
	v_mfma_f32_16x16x32_bf16 v[66:69], v[188:191], v[244:247], v[66:69]
	v_mfma_f32_16x16x32_bf16 v[122:125], v[184:187], v[200:203], v[122:125]
	v_mfma_f32_16x16x32_bf16 v[114:117], v[192:195], v[200:203], v[114:117]
	v_mfma_f32_16x16x32_bf16 v[106:109], v[184:187], v[220:223], v[106:109]
	v_mfma_f32_16x16x32_bf16 v[98:101], v[192:195], v[220:223], v[98:101]
	v_mfma_f32_16x16x32_bf16 v[90:93], v[184:187], v[240:243], v[90:93]
	v_mfma_f32_16x16x32_bf16 v[82:85], v[192:195], v[240:243], v[82:85]
	v_mfma_f32_16x16x32_bf16 v[74:77], v[184:187], v[248:251], v[74:77]
	v_mfma_f32_16x16x32_bf16 v[66:69], v[192:195], v[248:251], v[66:69]
	s_barrier
	s_add_i32 s36, s57, s44
	v_lshl_add_u64 v[146:147], v[146:147], 0, s[96:97]
	s_mov_b32 m0, s36
	ds_read_b128 v[196:199], v157 offset:49152
	ds_read_b128 v[200:203], v157 offset:50176
	ds_read_b128 v[204:207], v157 offset:51200
	ds_read_b128 v[220:223], v157 offset:52224
	ds_read_b128 v[236:239], v157 offset:53248
	ds_read_b128 v[240:243], v157 offset:54272
	ds_read_b128 v[244:247], v157 offset:55296
	ds_read_b128 v[248:251], v157 offset:56320
	global_load_lds_dwordx4 v[146:147], off
	s_add_i32 m0, s36, 0x2000
	s_add_u32 s34, s34, 0x40080
	v_lshl_add_u64 v[146:147], v[208:209], 0, s[96:97]
	s_addc_u32 s35, s35, 0
	s_add_i32 s36, s58, s44
	global_load_lds_dwordx4 v[146:147], off
	s_mov_b32 m0, s36
	s_nop 0
	global_load_lds_dwordx4 v134, s[34:35]
	s_add_i32 m0, s36, 0x2000
	s_nop 0
	global_load_lds_dwordx4 v130, s[34:35]
	s_mov_b32 m0, s52
	v_lshl_add_u64 v[146:147], v[224:225], 0, s[96:97]
	global_load_lds_dwordx4 v[146:147], off
	s_mov_b32 m0, s53
	v_lshl_add_u64 v[146:147], v[230:231], 0, s[96:97]
	global_load_lds_dwordx4 v[146:147], off
	s_waitcnt vmcnt(8)
	s_waitcnt lgkmcnt(0)
	s_barrier
	v_mfma_f32_16x16x32_bf16 v[62:65], v[142:145], v[196:199], v[62:65]
	v_mfma_f32_16x16x32_bf16 v[54:57], v[172:175], v[196:199], v[54:57]
	v_mfma_f32_16x16x32_bf16 v[46:49], v[142:145], v[204:207], v[46:49]
	v_mfma_f32_16x16x32_bf16 v[38:41], v[172:175], v[204:207], v[38:41]
	v_mfma_f32_16x16x32_bf16 v[30:33], v[142:145], v[236:239], v[30:33]
	v_mfma_f32_16x16x32_bf16 v[22:25], v[172:175], v[236:239], v[22:25]
	v_mfma_f32_16x16x32_bf16 v[14:17], v[142:145], v[244:247], v[14:17]
	v_mfma_f32_16x16x32_bf16 v[6:9], v[172:175], v[244:247], v[6:9]
	v_mfma_f32_16x16x32_bf16 v[62:65], v[168:171], v[200:203], v[62:65]
	v_mfma_f32_16x16x32_bf16 v[54:57], v[176:179], v[200:203], v[54:57]
	v_mfma_f32_16x16x32_bf16 v[46:49], v[168:171], v[220:223], v[46:49]
	v_mfma_f32_16x16x32_bf16 v[38:41], v[176:179], v[220:223], v[38:41]
	v_mfma_f32_16x16x32_bf16 v[30:33], v[168:171], v[240:243], v[30:33]
	v_mfma_f32_16x16x32_bf16 v[22:25], v[176:179], v[240:243], v[22:25]
	v_mfma_f32_16x16x32_bf16 v[14:17], v[168:171], v[248:251], v[14:17]
	v_mfma_f32_16x16x32_bf16 v[6:9], v[176:179], v[248:251], v[6:9]
	v_mfma_f32_16x16x32_bf16 v[58:61], v[180:183], v[196:199], v[58:61]
	v_mfma_f32_16x16x32_bf16 v[50:53], v[188:191], v[196:199], v[50:53]
	v_mfma_f32_16x16x32_bf16 v[42:45], v[180:183], v[204:207], v[42:45]
	v_mfma_f32_16x16x32_bf16 v[34:37], v[188:191], v[204:207], v[34:37]
	v_mfma_f32_16x16x32_bf16 v[26:29], v[180:183], v[236:239], v[26:29]
	v_mfma_f32_16x16x32_bf16 v[18:21], v[188:191], v[236:239], v[18:21]
	v_mfma_f32_16x16x32_bf16 v[10:13], v[180:183], v[244:247], v[10:13]
	v_mfma_f32_16x16x32_bf16 v[2:5], v[188:191], v[244:247], v[2:5]
	v_mfma_f32_16x16x32_bf16 v[58:61], v[184:187], v[200:203], v[58:61]
	v_mfma_f32_16x16x32_bf16 v[50:53], v[192:195], v[200:203], v[50:53]
	v_mfma_f32_16x16x32_bf16 v[42:45], v[184:187], v[220:223], v[42:45]
	v_mfma_f32_16x16x32_bf16 v[34:37], v[192:195], v[220:223], v[34:37]
	v_mfma_f32_16x16x32_bf16 v[26:29], v[184:187], v[240:243], v[26:29]
	v_mfma_f32_16x16x32_bf16 v[18:21], v[192:195], v[240:243], v[18:21]
	v_mfma_f32_16x16x32_bf16 v[10:13], v[184:187], v[248:251], v[10:13]
	v_mfma_f32_16x16x32_bf16 v[2:5], v[192:195], v[248:251], v[2:5]
	s_barrier
	s_add_i32 s56, s56, 2
	s_add_u32 s41, s41, 0x100
	s_addc_u32 s43, s43, 0
	s_add_u32 s30, s30, 0x100
	s_addc_u32 s31, s31, 0
	s_cmp_gt_u32 s56, 13
.LBB0_363:
	s_add_u32 s34, s30, 0xfffc0080
	s_addc_u32 s35, s31, -1
	s_add_i32 s57, 0, 0x10000
	s_cmp_eq_u32 s56, 12
	s_cselect_b32 s37, s23, s35
	s_cselect_b32 s36, s39, s34
	s_cselect_b32 s35, s21, s43
	s_cselect_b32 s34, s40, s41
	s_add_i32 s60, 0, 0x14000
	ds_read_b128 v[142:145], v155
	ds_read_b128 v[168:171], v155 offset:1024
	ds_read_b128 v[172:175], v155 offset:2048
	ds_read_b128 v[176:179], v155 offset:3072
	ds_read_b128 v[180:183], v155 offset:16384
	ds_read_b128 v[184:187], v155 offset:17408
	ds_read_b128 v[188:191], v155 offset:18432
	ds_read_b128 v[192:195], v155 offset:19456
	s_add_i32 m0, s48, 0xc000
	ds_read_b128 v[196:199], v157
	ds_read_b128 v[200:203], v157 offset:1024
	ds_read_b128 v[204:207], v157 offset:2048
	ds_read_b128 v[220:223], v157 offset:3072
	ds_read_b128 v[236:239], v157 offset:4096
	ds_read_b128 v[240:243], v157 offset:5120
	ds_read_b128 v[244:247], v157 offset:6144
	global_load_lds_dwordx4 v140, s[30:31]
	s_add_i32 m0, s48, 0xe000
	ds_read_b128 v[248:251], v157 offset:7168
	global_load_lds_dwordx4 v138, s[30:31]
	s_waitcnt vmcnt(8)
	s_waitcnt lgkmcnt(0)
	s_barrier
	v_mfma_f32_16x16x32_bf16 v[126:129], v[142:145], v[196:199], v[126:129]
	v_mfma_f32_16x16x32_bf16 v[118:121], v[172:175], v[196:199], v[118:121]
	v_mfma_f32_16x16x32_bf16 v[110:113], v[142:145], v[204:207], v[110:113]
	v_mfma_f32_16x16x32_bf16 v[102:105], v[172:175], v[204:207], v[102:105]
	v_mfma_f32_16x16x32_bf16 v[94:97], v[142:145], v[236:239], v[94:97]
	v_mfma_f32_16x16x32_bf16 v[86:89], v[172:175], v[236:239], v[86:89]
	v_mfma_f32_16x16x32_bf16 v[78:81], v[142:145], v[244:247], v[78:81]
	v_mfma_f32_16x16x32_bf16 v[70:73], v[172:175], v[244:247], v[70:73]
	v_mfma_f32_16x16x32_bf16 v[126:129], v[168:171], v[200:203], v[126:129]
	v_mfma_f32_16x16x32_bf16 v[118:121], v[176:179], v[200:203], v[118:121]
	v_mfma_f32_16x16x32_bf16 v[110:113], v[168:171], v[220:223], v[110:113]
	v_mfma_f32_16x16x32_bf16 v[102:105], v[176:179], v[220:223], v[102:105]
	v_mfma_f32_16x16x32_bf16 v[94:97], v[168:171], v[240:243], v[94:97]
	v_mfma_f32_16x16x32_bf16 v[86:89], v[176:179], v[240:243], v[86:89]
	v_mfma_f32_16x16x32_bf16 v[78:81], v[168:171], v[248:251], v[78:81]
	v_mfma_f32_16x16x32_bf16 v[70:73], v[176:179], v[248:251], v[70:73]
	v_mfma_f32_16x16x32_bf16 v[122:125], v[180:183], v[196:199], v[122:125]
	v_mfma_f32_16x16x32_bf16 v[114:117], v[188:191], v[196:199], v[114:117]
	v_mfma_f32_16x16x32_bf16 v[106:109], v[180:183], v[204:207], v[106:109]
	v_mfma_f32_16x16x32_bf16 v[98:101], v[188:191], v[204:207], v[98:101]
	v_mfma_f32_16x16x32_bf16 v[90:93], v[180:183], v[236:239], v[90:93]
	v_mfma_f32_16x16x32_bf16 v[82:85], v[188:191], v[236:239], v[82:85]
	v_mfma_f32_16x16x32_bf16 v[74:77], v[180:183], v[244:247], v[74:77]
	v_mfma_f32_16x16x32_bf16 v[66:69], v[188:191], v[244:247], v[66:69]
	v_mfma_f32_16x16x32_bf16 v[122:125], v[184:187], v[200:203], v[122:125]
	v_mfma_f32_16x16x32_bf16 v[114:117], v[192:195], v[200:203], v[114:117]
	v_mfma_f32_16x16x32_bf16 v[106:109], v[184:187], v[220:223], v[106:109]
	v_mfma_f32_16x16x32_bf16 v[98:101], v[192:195], v[220:223], v[98:101]
	v_mfma_f32_16x16x32_bf16 v[90:93], v[184:187], v[240:243], v[90:93]
	v_mfma_f32_16x16x32_bf16 v[82:85], v[192:195], v[240:243], v[82:85]
	v_mfma_f32_16x16x32_bf16 v[74:77], v[184:187], v[248:251], v[74:77]
	v_mfma_f32_16x16x32_bf16 v[66:69], v[192:195], v[248:251], v[66:69]
	s_barrier
	s_add_i32 s57, s57, s44
	s_mov_b32 m0, s57
	ds_read_b128 v[196:199], v157 offset:16384
	ds_read_b128 v[200:203], v157 offset:17408
	ds_read_b128 v[204:207], v157 offset:18432
	ds_read_b128 v[220:223], v157 offset:19456
	global_load_lds_dwordx4 v134, s[34:35]
	s_add_i32 m0, s57, 0x2000
	s_add_u32 s58, s34, 0x40000
	s_addc_u32 s59, s35, 0
	s_add_i32 s57, s60, s44
	global_load_lds_dwordx4 v130, s[34:35]
	s_mov_b32 m0, s57
	ds_read_b128 v[236:239], v157 offset:20480
	global_load_lds_dwordx4 v134, s[58:59]
	s_add_i32 m0, s57, 0x2000
	ds_read_b128 v[240:243], v157 offset:21504
	global_load_lds_dwordx4 v130, s[58:59]
	s_mov_b32 m0, s48
	ds_read_b128 v[244:247], v157 offset:22528
	global_load_lds_dwordx4 v136, s[36:37]
	s_mov_b32 m0, s49
	ds_read_b128 v[248:251], v157 offset:23552
	global_load_lds_dwordx4 v132, s[36:37]
	s_waitcnt vmcnt(8)
	s_waitcnt lgkmcnt(0)
	s_barrier
	v_mfma_f32_16x16x32_bf16 v[62:65], v[142:145], v[196:199], v[62:65]
	v_mfma_f32_16x16x32_bf16 v[54:57], v[172:175], v[196:199], v[54:57]
	v_mfma_f32_16x16x32_bf16 v[46:49], v[142:145], v[204:207], v[46:49]
	v_mfma_f32_16x16x32_bf16 v[38:41], v[172:175], v[204:207], v[38:41]
	v_mfma_f32_16x16x32_bf16 v[30:33], v[142:145], v[236:239], v[30:33]
	v_mfma_f32_16x16x32_bf16 v[22:25], v[172:175], v[236:239], v[22:25]
	v_mfma_f32_16x16x32_bf16 v[14:17], v[142:145], v[244:247], v[14:17]
	v_mfma_f32_16x16x32_bf16 v[6:9], v[172:175], v[244:247], v[6:9]
	v_mfma_f32_16x16x32_bf16 v[62:65], v[168:171], v[200:203], v[62:65]
	v_mfma_f32_16x16x32_bf16 v[54:57], v[176:179], v[200:203], v[54:57]
	v_mfma_f32_16x16x32_bf16 v[46:49], v[168:171], v[220:223], v[46:49]
	v_mfma_f32_16x16x32_bf16 v[38:41], v[176:179], v[220:223], v[38:41]
	v_mfma_f32_16x16x32_bf16 v[30:33], v[168:171], v[240:243], v[30:33]
	v_mfma_f32_16x16x32_bf16 v[22:25], v[176:179], v[240:243], v[22:25]
	v_mfma_f32_16x16x32_bf16 v[14:17], v[168:171], v[248:251], v[14:17]
	v_mfma_f32_16x16x32_bf16 v[6:9], v[176:179], v[248:251], v[6:9]
	v_mfma_f32_16x16x32_bf16 v[58:61], v[180:183], v[196:199], v[58:61]
	v_mfma_f32_16x16x32_bf16 v[50:53], v[188:191], v[196:199], v[50:53]
	v_mfma_f32_16x16x32_bf16 v[42:45], v[180:183], v[204:207], v[42:45]
	v_mfma_f32_16x16x32_bf16 v[34:37], v[188:191], v[204:207], v[34:37]
	v_mfma_f32_16x16x32_bf16 v[26:29], v[180:183], v[236:239], v[26:29]
	v_mfma_f32_16x16x32_bf16 v[18:21], v[188:191], v[236:239], v[18:21]
	v_mfma_f32_16x16x32_bf16 v[10:13], v[180:183], v[244:247], v[10:13]
	v_mfma_f32_16x16x32_bf16 v[2:5], v[188:191], v[244:247], v[2:5]
	v_mfma_f32_16x16x32_bf16 v[58:61], v[184:187], v[200:203], v[58:61]
	v_mfma_f32_16x16x32_bf16 v[50:53], v[192:195], v[200:203], v[50:53]
	v_mfma_f32_16x16x32_bf16 v[42:45], v[184:187], v[220:223], v[42:45]
	v_mfma_f32_16x16x32_bf16 v[34:37], v[192:195], v[220:223], v[34:37]
	v_mfma_f32_16x16x32_bf16 v[26:29], v[184:187], v[240:243], v[26:29]
	v_mfma_f32_16x16x32_bf16 v[18:21], v[192:195], v[240:243], v[18:21]
	v_mfma_f32_16x16x32_bf16 v[10:13], v[184:187], v[248:251], v[10:13]
	v_mfma_f32_16x16x32_bf16 v[2:5], v[192:195], v[248:251], v[2:5]
	s_barrier
	s_add_i32 s57, 0, 0x18000
	s_add_i32 s58, 0, 0x1c000
	ds_read_b128 v[142:145], v155 offset:32768
	ds_read_b128 v[168:171], v155 offset:33792
	ds_read_b128 v[172:175], v155 offset:34816
	ds_read_b128 v[176:179], v155 offset:35840
	ds_read_b128 v[180:183], v155 offset:49152
	ds_read_b128 v[184:187], v155 offset:50176
	ds_read_b128 v[188:191], v155 offset:51200
	ds_read_b128 v[192:195], v155 offset:52224
	s_add_u32 s36, s36, 0x40000
	s_addc_u32 s37, s37, 0
	s_mov_b32 m0, s50
	ds_read_b128 v[196:199], v157 offset:32768
	ds_read_b128 v[200:203], v157 offset:33792
	ds_read_b128 v[204:207], v157 offset:34816
	ds_read_b128 v[220:223], v157 offset:35840
	ds_read_b128 v[236:239], v157 offset:36864
	ds_read_b128 v[240:243], v157 offset:37888
	ds_read_b128 v[244:247], v157 offset:38912
	global_load_lds_dwordx4 v136, s[36:37]
	s_mov_b32 m0, s51
	ds_read_b128 v[248:251], v157 offset:39936
	global_load_lds_dwordx4 v132, s[36:37]
	s_waitcnt vmcnt(8)
	s_waitcnt lgkmcnt(0)
	s_barrier
	v_mfma_f32_16x16x32_bf16 v[126:129], v[142:145], v[196:199], v[126:129]
	v_mfma_f32_16x16x32_bf16 v[118:121], v[172:175], v[196:199], v[118:121]
	v_mfma_f32_16x16x32_bf16 v[110:113], v[142:145], v[204:207], v[110:113]
	v_mfma_f32_16x16x32_bf16 v[102:105], v[172:175], v[204:207], v[102:105]
	v_mfma_f32_16x16x32_bf16 v[94:97], v[142:145], v[236:239], v[94:97]
	v_mfma_f32_16x16x32_bf16 v[86:89], v[172:175], v[236:239], v[86:89]
	v_mfma_f32_16x16x32_bf16 v[78:81], v[142:145], v[244:247], v[78:81]
	v_mfma_f32_16x16x32_bf16 v[70:73], v[172:175], v[244:247], v[70:73]
	v_mfma_f32_16x16x32_bf16 v[126:129], v[168:171], v[200:203], v[126:129]
	v_mfma_f32_16x16x32_bf16 v[118:121], v[176:179], v[200:203], v[118:121]
	v_mfma_f32_16x16x32_bf16 v[110:113], v[168:171], v[220:223], v[110:113]
	v_mfma_f32_16x16x32_bf16 v[102:105], v[176:179], v[220:223], v[102:105]
	v_mfma_f32_16x16x32_bf16 v[94:97], v[168:171], v[240:243], v[94:97]
	v_mfma_f32_16x16x32_bf16 v[86:89], v[176:179], v[240:243], v[86:89]
	v_mfma_f32_16x16x32_bf16 v[78:81], v[168:171], v[248:251], v[78:81]
	v_mfma_f32_16x16x32_bf16 v[70:73], v[176:179], v[248:251], v[70:73]
	v_mfma_f32_16x16x32_bf16 v[122:125], v[180:183], v[196:199], v[122:125]
	v_mfma_f32_16x16x32_bf16 v[114:117], v[188:191], v[196:199], v[114:117]
	v_mfma_f32_16x16x32_bf16 v[106:109], v[180:183], v[204:207], v[106:109]
	v_mfma_f32_16x16x32_bf16 v[98:101], v[188:191], v[204:207], v[98:101]
	v_mfma_f32_16x16x32_bf16 v[90:93], v[180:183], v[236:239], v[90:93]
	v_mfma_f32_16x16x32_bf16 v[82:85], v[188:191], v[236:239], v[82:85]
	v_mfma_f32_16x16x32_bf16 v[74:77], v[180:183], v[244:247], v[74:77]
	v_mfma_f32_16x16x32_bf16 v[66:69], v[188:191], v[244:247], v[66:69]
	v_mfma_f32_16x16x32_bf16 v[122:125], v[184:187], v[200:203], v[122:125]
	v_mfma_f32_16x16x32_bf16 v[114:117], v[192:195], v[200:203], v[114:117]
	v_mfma_f32_16x16x32_bf16 v[106:109], v[184:187], v[220:223], v[106:109]
	v_mfma_f32_16x16x32_bf16 v[98:101], v[192:195], v[220:223], v[98:101]
	v_mfma_f32_16x16x32_bf16 v[90:93], v[184:187], v[240:243], v[90:93]
	v_mfma_f32_16x16x32_bf16 v[82:85], v[192:195], v[240:243], v[82:85]
	v_mfma_f32_16x16x32_bf16 v[74:77], v[184:187], v[248:251], v[74:77]
	v_mfma_f32_16x16x32_bf16 v[66:69], v[192:195], v[248:251], v[66:69]
	s_barrier
	s_add_u32 s100, s36, 0xfffc0080
	s_addc_u32 s101, s37, -1
	s_add_i32 s36, s57, s44
	s_add_u32 s34, s34, 0x80
	s_mov_b32 m0, s36
	s_addc_u32 s35, s35, 0
	ds_read_b128 v[196:199], v157 offset:49152
	ds_read_b128 v[200:203], v157 offset:50176
	ds_read_b128 v[204:207], v157 offset:51200
	ds_read_b128 v[220:223], v157 offset:52224
	ds_read_b128 v[236:239], v157 offset:53248
	global_load_lds_dwordx4 v134, s[34:35]
	s_add_i32 m0, s36, 0x2000
	s_add_i32 s36, s58, s44
	global_load_lds_dwordx4 v130, s[34:35]
	s_mov_b32 m0, s36
	s_add_u32 s34, s34, 0x40000
	s_addc_u32 s35, s35, 0
	global_load_lds_dwordx4 v134, s[34:35]
	s_add_i32 m0, s36, 0x2000
	ds_read_b128 v[240:243], v157 offset:54272
	global_load_lds_dwordx4 v130, s[34:35]
	s_mov_b32 m0, s52
	ds_read_b128 v[244:247], v157 offset:55296
	global_load_lds_dwordx4 v136, s[100:101]
	s_mov_b32 m0, s53
	ds_read_b128 v[248:251], v157 offset:56320
	global_load_lds_dwordx4 v132, s[100:101]
	s_waitcnt vmcnt(8)
	s_waitcnt lgkmcnt(0)
	s_barrier
	v_mfma_f32_16x16x32_bf16 v[62:65], v[142:145], v[196:199], v[62:65]
	v_mfma_f32_16x16x32_bf16 v[54:57], v[172:175], v[196:199], v[54:57]
	v_mfma_f32_16x16x32_bf16 v[46:49], v[142:145], v[204:207], v[46:49]
	v_mfma_f32_16x16x32_bf16 v[38:41], v[172:175], v[204:207], v[38:41]
	v_mfma_f32_16x16x32_bf16 v[30:33], v[142:145], v[236:239], v[30:33]
	v_mfma_f32_16x16x32_bf16 v[22:25], v[172:175], v[236:239], v[22:25]
	v_mfma_f32_16x16x32_bf16 v[14:17], v[142:145], v[244:247], v[14:17]
	v_mfma_f32_16x16x32_bf16 v[6:9], v[172:175], v[244:247], v[6:9]
	v_mfma_f32_16x16x32_bf16 v[62:65], v[168:171], v[200:203], v[62:65]
	v_mfma_f32_16x16x32_bf16 v[54:57], v[176:179], v[200:203], v[54:57]
	v_mfma_f32_16x16x32_bf16 v[46:49], v[168:171], v[220:223], v[46:49]
	v_mfma_f32_16x16x32_bf16 v[38:41], v[176:179], v[220:223], v[38:41]
	v_mfma_f32_16x16x32_bf16 v[30:33], v[168:171], v[240:243], v[30:33]
	v_mfma_f32_16x16x32_bf16 v[22:25], v[176:179], v[240:243], v[22:25]
	v_mfma_f32_16x16x32_bf16 v[14:17], v[168:171], v[248:251], v[14:17]
	v_mfma_f32_16x16x32_bf16 v[6:9], v[176:179], v[248:251], v[6:9]
	v_mfma_f32_16x16x32_bf16 v[58:61], v[180:183], v[196:199], v[58:61]
	v_mfma_f32_16x16x32_bf16 v[50:53], v[188:191], v[196:199], v[50:53]
	v_mfma_f32_16x16x32_bf16 v[42:45], v[180:183], v[204:207], v[42:45]
	v_mfma_f32_16x16x32_bf16 v[34:37], v[188:191], v[204:207], v[34:37]
	v_mfma_f32_16x16x32_bf16 v[26:29], v[180:183], v[236:239], v[26:29]
	v_mfma_f32_16x16x32_bf16 v[18:21], v[188:191], v[236:239], v[18:21]
	v_mfma_f32_16x16x32_bf16 v[10:13], v[180:183], v[244:247], v[10:13]
	v_mfma_f32_16x16x32_bf16 v[2:5], v[188:191], v[244:247], v[2:5]
	v_mfma_f32_16x16x32_bf16 v[58:61], v[184:187], v[200:203], v[58:61]
	v_mfma_f32_16x16x32_bf16 v[50:53], v[192:195], v[200:203], v[50:53]
	v_mfma_f32_16x16x32_bf16 v[42:45], v[184:187], v[220:223], v[42:45]
	v_mfma_f32_16x16x32_bf16 v[34:37], v[192:195], v[220:223], v[34:37]
	v_mfma_f32_16x16x32_bf16 v[26:29], v[184:187], v[240:243], v[26:29]
	v_mfma_f32_16x16x32_bf16 v[18:21], v[192:195], v[240:243], v[18:21]
	v_mfma_f32_16x16x32_bf16 v[10:13], v[184:187], v[248:251], v[10:13]
	v_mfma_f32_16x16x32_bf16 v[2:5], v[192:195], v[248:251], v[2:5]
	s_barrier
	s_add_i32 s56, s56, 2
	s_add_u32 s41, s41, 0x100
	s_addc_u32 s43, s43, 0
	s_add_u32 s30, s30, 0x100
	s_addc_u32 s31, s31, 0
	s_cmp_gt_u32 s56, 13
	s_cbranch_scc0 .LBB0_363
	s_and_b64 vcc, exec, s[16:17]
	s_cbranch_vccz .LBB0_366
	s_barrier

.LBB0_476:
	s_add_i32 s63, s31, 2
	s_add_u32 s38, s28, s36
	s_addc_u32 s39, s29, s37
	s_add_u32 s64, s26, s36
	s_addc_u32 s65, s27, s37
	s_add_i32 s66, 0, 0x10000
	s_cmp_eq_u32 s59, s31
	s_cselect_b32 s39, s9, s39
	s_cselect_b32 s38, s8, s38
	s_cselect_b32 s65, s35, s65
	s_cselect_b32 s64, s34, s64
	s_add_i32 s31, 0, 0x14000
	ds_read_b128 v[148:151], v146
	ds_read_b128 v[152:155], v146 offset:1024
	ds_read_b128 v[156:159], v146 offset:2048
	ds_read_b128 v[160:163], v146 offset:3072
	ds_read_b128 v[164:167], v146 offset:16384
	ds_read_b128 v[168:171], v146 offset:17408
	ds_read_b128 v[172:175], v146 offset:18432
	ds_read_b128 v[176:179], v146 offset:19456
	s_add_i32 m0, s51, 0xc000
	ds_read_b128 v[180:183], v147
	ds_read_b128 v[184:187], v147 offset:1024
	ds_read_b128 v[188:191], v147 offset:2048
	ds_read_b128 v[192:195], v147 offset:3072
	ds_read_b128 v[196:199], v147 offset:4096
	ds_read_b128 v[200:203], v147 offset:5120
	ds_read_b128 v[204:207], v147 offset:6144
	global_load_lds_dwordx4 v142, s[28:29]
	s_add_i32 m0, s51, 0xe000
	ds_read_b128 v[220:223], v147 offset:7168
	global_load_lds_dwordx4 v144, s[28:29]
	s_waitcnt vmcnt(8)
	s_waitcnt lgkmcnt(0)
	s_barrier
	v_mfma_f32_16x16x32_bf16 v[126:129], v[148:151], v[180:183], v[126:129]
	v_mfma_f32_16x16x32_bf16 v[122:125], v[156:159], v[180:183], v[122:125]
	v_mfma_f32_16x16x32_bf16 v[110:113], v[148:151], v[188:191], v[110:113]
	v_mfma_f32_16x16x32_bf16 v[106:109], v[156:159], v[188:191], v[106:109]
	v_mfma_f32_16x16x32_bf16 v[94:97], v[148:151], v[196:199], v[94:97]
	v_mfma_f32_16x16x32_bf16 v[90:93], v[156:159], v[196:199], v[90:93]
	v_mfma_f32_16x16x32_bf16 v[78:81], v[148:151], v[204:207], v[78:81]
	v_mfma_f32_16x16x32_bf16 v[74:77], v[156:159], v[204:207], v[74:77]
	v_mfma_f32_16x16x32_bf16 v[126:129], v[152:155], v[184:187], v[126:129]
	v_mfma_f32_16x16x32_bf16 v[122:125], v[160:163], v[184:187], v[122:125]
	v_mfma_f32_16x16x32_bf16 v[110:113], v[152:155], v[192:195], v[110:113]
	v_mfma_f32_16x16x32_bf16 v[106:109], v[160:163], v[192:195], v[106:109]
	v_mfma_f32_16x16x32_bf16 v[94:97], v[152:155], v[200:203], v[94:97]
	v_mfma_f32_16x16x32_bf16 v[90:93], v[160:163], v[200:203], v[90:93]
	v_mfma_f32_16x16x32_bf16 v[78:81], v[152:155], v[220:223], v[78:81]
	v_mfma_f32_16x16x32_bf16 v[74:77], v[160:163], v[220:223], v[74:77]
	v_mfma_f32_16x16x32_bf16 v[118:121], v[164:167], v[180:183], v[118:121]
	v_mfma_f32_16x16x32_bf16 v[114:117], v[172:175], v[180:183], v[114:117]
	v_mfma_f32_16x16x32_bf16 v[102:105], v[164:167], v[188:191], v[102:105]
	v_mfma_f32_16x16x32_bf16 v[98:101], v[172:175], v[188:191], v[98:101]
	v_mfma_f32_16x16x32_bf16 v[86:89], v[164:167], v[196:199], v[86:89]
	v_mfma_f32_16x16x32_bf16 v[82:85], v[172:175], v[196:199], v[82:85]
	v_mfma_f32_16x16x32_bf16 v[70:73], v[164:167], v[204:207], v[70:73]
	v_mfma_f32_16x16x32_bf16 v[66:69], v[172:175], v[204:207], v[66:69]
	v_mfma_f32_16x16x32_bf16 v[118:121], v[168:171], v[184:187], v[118:121]
	v_mfma_f32_16x16x32_bf16 v[114:117], v[176:179], v[184:187], v[114:117]
	v_mfma_f32_16x16x32_bf16 v[102:105], v[168:171], v[192:195], v[102:105]
	v_mfma_f32_16x16x32_bf16 v[98:101], v[176:179], v[192:195], v[98:101]
	v_mfma_f32_16x16x32_bf16 v[86:89], v[168:171], v[200:203], v[86:89]
	v_mfma_f32_16x16x32_bf16 v[82:85], v[176:179], v[200:203], v[82:85]
	v_mfma_f32_16x16x32_bf16 v[70:73], v[168:171], v[220:223], v[70:73]
	v_mfma_f32_16x16x32_bf16 v[66:69], v[176:179], v[220:223], v[66:69]
	s_barrier
	s_add_i32 s66, s66, s47
	s_mov_b32 m0, s66
	ds_read_b128 v[180:183], v147 offset:16384
	ds_read_b128 v[184:187], v147 offset:17408
	ds_read_b128 v[188:191], v147 offset:18432
	ds_read_b128 v[192:195], v147 offset:19456
	global_load_lds_dwordx4 v132, s[64:65]
	s_add_i32 m0, s66, 0x2000
	s_mov_b64 s[100:101], s[64:65]
	s_add_u32 s64, s64, s45
	s_addc_u32 s65, s65, 0
	s_add_i32 s31, s31, s47
	global_load_lds_dwordx4 v136, s[100:101]
	s_mov_b32 m0, s31
	ds_read_b128 v[196:199], v147 offset:20480
	global_load_lds_dwordx4 v132, s[64:65]
	s_add_i32 m0, s31, 0x2000
	ds_read_b128 v[200:203], v147 offset:21504
	global_load_lds_dwordx4 v136, s[64:65]
	s_mov_b32 m0, s51
	ds_read_b128 v[204:207], v147 offset:22528
	global_load_lds_dwordx4 v130, s[38:39]
	s_mov_b32 m0, s52
	ds_read_b128 v[220:223], v147 offset:23552
	global_load_lds_dwordx4 v134, s[38:39]
	s_waitcnt vmcnt(8)
	s_waitcnt lgkmcnt(0)
	s_barrier
	v_mfma_f32_16x16x32_bf16 v[62:65], v[148:151], v[180:183], v[62:65]
	v_mfma_f32_16x16x32_bf16 v[58:61], v[156:159], v[180:183], v[58:61]
	v_mfma_f32_16x16x32_bf16 v[46:49], v[148:151], v[188:191], v[46:49]
	v_mfma_f32_16x16x32_bf16 v[42:45], v[156:159], v[188:191], v[42:45]
	v_mfma_f32_16x16x32_bf16 v[30:33], v[148:151], v[196:199], v[30:33]
	v_mfma_f32_16x16x32_bf16 v[26:29], v[156:159], v[196:199], v[26:29]
	v_mfma_f32_16x16x32_bf16 v[14:17], v[148:151], v[204:207], v[14:17]
	v_mfma_f32_16x16x32_bf16 v[10:13], v[156:159], v[204:207], v[10:13]
	v_mfma_f32_16x16x32_bf16 v[62:65], v[152:155], v[184:187], v[62:65]
	v_mfma_f32_16x16x32_bf16 v[58:61], v[160:163], v[184:187], v[58:61]
	v_mfma_f32_16x16x32_bf16 v[46:49], v[152:155], v[192:195], v[46:49]
	v_mfma_f32_16x16x32_bf16 v[42:45], v[160:163], v[192:195], v[42:45]
	v_mfma_f32_16x16x32_bf16 v[30:33], v[152:155], v[200:203], v[30:33]
	v_mfma_f32_16x16x32_bf16 v[26:29], v[160:163], v[200:203], v[26:29]
	v_mfma_f32_16x16x32_bf16 v[14:17], v[152:155], v[220:223], v[14:17]
	v_mfma_f32_16x16x32_bf16 v[10:13], v[160:163], v[220:223], v[10:13]
	v_mfma_f32_16x16x32_bf16 v[54:57], v[164:167], v[180:183], v[54:57]
	v_mfma_f32_16x16x32_bf16 v[50:53], v[172:175], v[180:183], v[50:53]
	v_mfma_f32_16x16x32_bf16 v[38:41], v[164:167], v[188:191], v[38:41]
	v_mfma_f32_16x16x32_bf16 v[34:37], v[172:175], v[188:191], v[34:37]
	v_mfma_f32_16x16x32_bf16 v[22:25], v[164:167], v[196:199], v[22:25]
	v_mfma_f32_16x16x32_bf16 v[18:21], v[172:175], v[196:199], v[18:21]
	v_mfma_f32_16x16x32_bf16 v[6:9], v[164:167], v[204:207], v[6:9]
	v_mfma_f32_16x16x32_bf16 v[2:5], v[172:175], v[204:207], v[2:5]
	v_mfma_f32_16x16x32_bf16 v[54:57], v[168:171], v[184:187], v[54:57]
	v_mfma_f32_16x16x32_bf16 v[50:53], v[176:179], v[184:187], v[50:53]
	v_mfma_f32_16x16x32_bf16 v[38:41], v[168:171], v[192:195], v[38:41]
	v_mfma_f32_16x16x32_bf16 v[34:37], v[176:179], v[192:195], v[34:37]
	v_mfma_f32_16x16x32_bf16 v[22:25], v[168:171], v[200:203], v[22:25]
	v_mfma_f32_16x16x32_bf16 v[18:21], v[176:179], v[200:203], v[18:21]
	v_mfma_f32_16x16x32_bf16 v[6:9], v[168:171], v[220:223], v[6:9]
	v_mfma_f32_16x16x32_bf16 v[2:5], v[176:179], v[220:223], v[2:5]
	s_barrier
	s_add_i32 s31, 0, 0x18000
	s_add_i32 s64, 0, 0x1c000
	ds_read_b128 v[148:151], v146 offset:32768
	ds_read_b128 v[152:155], v146 offset:33792
	ds_read_b128 v[156:159], v146 offset:34816
	ds_read_b128 v[160:163], v146 offset:35840
	ds_read_b128 v[164:167], v146 offset:49152
	ds_read_b128 v[168:171], v146 offset:50176
	ds_read_b128 v[172:175], v146 offset:51200
	ds_read_b128 v[176:179], v146 offset:52224
	s_add_u32 s38, s38, s45
	s_addc_u32 s39, s39, 0
	s_mov_b32 m0, s53
	ds_read_b128 v[180:183], v147 offset:32768
	ds_read_b128 v[184:187], v147 offset:33792
	ds_read_b128 v[188:191], v147 offset:34816
	ds_read_b128 v[192:195], v147 offset:35840
	ds_read_b128 v[196:199], v147 offset:36864
	ds_read_b128 v[200:203], v147 offset:37888
	ds_read_b128 v[204:207], v147 offset:38912
	global_load_lds_dwordx4 v130, s[38:39]
	s_mov_b32 m0, s54
	ds_read_b128 v[220:223], v147 offset:39936
	global_load_lds_dwordx4 v134, s[38:39]
	s_waitcnt vmcnt(8)
	s_waitcnt lgkmcnt(0)
	s_barrier
	v_mfma_f32_16x16x32_bf16 v[126:129], v[148:151], v[180:183], v[126:129]
	v_mfma_f32_16x16x32_bf16 v[122:125], v[156:159], v[180:183], v[122:125]
	v_mfma_f32_16x16x32_bf16 v[110:113], v[148:151], v[188:191], v[110:113]
	v_mfma_f32_16x16x32_bf16 v[106:109], v[156:159], v[188:191], v[106:109]
	v_mfma_f32_16x16x32_bf16 v[94:97], v[148:151], v[196:199], v[94:97]
	v_mfma_f32_16x16x32_bf16 v[90:93], v[156:159], v[196:199], v[90:93]
	v_mfma_f32_16x16x32_bf16 v[78:81], v[148:151], v[204:207], v[78:81]
	v_mfma_f32_16x16x32_bf16 v[74:77], v[156:159], v[204:207], v[74:77]
	v_mfma_f32_16x16x32_bf16 v[126:129], v[152:155], v[184:187], v[126:129]
	v_mfma_f32_16x16x32_bf16 v[122:125], v[160:163], v[184:187], v[122:125]
	v_mfma_f32_16x16x32_bf16 v[110:113], v[152:155], v[192:195], v[110:113]
	v_mfma_f32_16x16x32_bf16 v[106:109], v[160:163], v[192:195], v[106:109]
	v_mfma_f32_16x16x32_bf16 v[94:97], v[152:155], v[200:203], v[94:97]
	v_mfma_f32_16x16x32_bf16 v[90:93], v[160:163], v[200:203], v[90:93]
	v_mfma_f32_16x16x32_bf16 v[78:81], v[152:155], v[220:223], v[78:81]
	v_mfma_f32_16x16x32_bf16 v[74:77], v[160:163], v[220:223], v[74:77]
	v_mfma_f32_16x16x32_bf16 v[118:121], v[164:167], v[180:183], v[118:121]
	v_mfma_f32_16x16x32_bf16 v[114:117], v[172:175], v[180:183], v[114:117]
	v_mfma_f32_16x16x32_bf16 v[102:105], v[164:167], v[188:191], v[102:105]
	v_mfma_f32_16x16x32_bf16 v[98:101], v[172:175], v[188:191], v[98:101]
	v_mfma_f32_16x16x32_bf16 v[86:89], v[164:167], v[196:199], v[86:89]
	v_mfma_f32_16x16x32_bf16 v[82:85], v[172:175], v[196:199], v[82:85]
	v_mfma_f32_16x16x32_bf16 v[70:73], v[164:167], v[204:207], v[70:73]
	v_mfma_f32_16x16x32_bf16 v[66:69], v[172:175], v[204:207], v[66:69]
	v_mfma_f32_16x16x32_bf16 v[118:121], v[168:171], v[184:187], v[118:121]
	v_mfma_f32_16x16x32_bf16 v[114:117], v[176:179], v[184:187], v[114:117]
	v_mfma_f32_16x16x32_bf16 v[102:105], v[168:171], v[192:195], v[102:105]
	v_mfma_f32_16x16x32_bf16 v[98:101], v[176:179], v[192:195], v[98:101]
	v_mfma_f32_16x16x32_bf16 v[86:89], v[168:171], v[200:203], v[86:89]
	v_mfma_f32_16x16x32_bf16 v[82:85], v[176:179], v[200:203], v[82:85]
	v_mfma_f32_16x16x32_bf16 v[70:73], v[168:171], v[220:223], v[70:73]
	v_mfma_f32_16x16x32_bf16 v[66:69], v[176:179], v[220:223], v[66:69]
	s_barrier
	s_add_i32 s31, s31, s47
	s_add_u32 s100, s100, 0x80
	s_addc_u32 s101, s101, 0
	s_mov_b32 m0, s31
	ds_read_b128 v[180:183], v147 offset:49152
	ds_read_b128 v[184:187], v147 offset:50176
	ds_read_b128 v[188:191], v147 offset:51200
	ds_read_b128 v[192:195], v147 offset:52224
	global_load_lds_dwordx4 v132, s[100:101]
	s_add_i32 m0, s31, 0x2000
	s_add_i32 s31, s64, s47
	global_load_lds_dwordx4 v136, s[100:101]
	s_add_u32 s100, s100, s45
	s_addc_u32 s101, s101, 0
	s_mov_b32 m0, s31
	ds_read_b128 v[196:199], v147 offset:53248
	global_load_lds_dwordx4 v132, s[100:101]
	s_add_i32 m0, s31, 0x2000
	ds_read_b128 v[200:203], v147 offset:54272
	global_load_lds_dwordx4 v136, s[100:101]
	s_sub_u32 s38, s38, s45
	s_subb_u32 s39, s39, 0
	s_add_u32 s38, s38, 0x80
	s_addc_u32 s39, s39, 0
	s_mov_b32 m0, s57
	ds_read_b128 v[204:207], v147 offset:55296
	global_load_lds_dwordx4 v130, s[38:39]
	s_mov_b32 m0, s58
	ds_read_b128 v[220:223], v147 offset:56320
	global_load_lds_dwordx4 v134, s[38:39]
	s_waitcnt vmcnt(8)
	s_waitcnt lgkmcnt(0)
	s_barrier
	v_mfma_f32_16x16x32_bf16 v[62:65], v[148:151], v[180:183], v[62:65]
	v_mfma_f32_16x16x32_bf16 v[58:61], v[156:159], v[180:183], v[58:61]
	v_mfma_f32_16x16x32_bf16 v[46:49], v[148:151], v[188:191], v[46:49]
	v_mfma_f32_16x16x32_bf16 v[42:45], v[156:159], v[188:191], v[42:45]
	v_mfma_f32_16x16x32_bf16 v[30:33], v[148:151], v[196:199], v[30:33]
	v_mfma_f32_16x16x32_bf16 v[26:29], v[156:159], v[196:199], v[26:29]
	v_mfma_f32_16x16x32_bf16 v[14:17], v[148:151], v[204:207], v[14:17]
	v_mfma_f32_16x16x32_bf16 v[10:13], v[156:159], v[204:207], v[10:13]
	v_mfma_f32_16x16x32_bf16 v[62:65], v[152:155], v[184:187], v[62:65]
	v_mfma_f32_16x16x32_bf16 v[58:61], v[160:163], v[184:187], v[58:61]
	v_mfma_f32_16x16x32_bf16 v[46:49], v[152:155], v[192:195], v[46:49]
	v_mfma_f32_16x16x32_bf16 v[42:45], v[160:163], v[192:195], v[42:45]
	v_mfma_f32_16x16x32_bf16 v[30:33], v[152:155], v[200:203], v[30:33]
	v_mfma_f32_16x16x32_bf16 v[26:29], v[160:163], v[200:203], v[26:29]
	v_mfma_f32_16x16x32_bf16 v[14:17], v[152:155], v[220:223], v[14:17]
	v_mfma_f32_16x16x32_bf16 v[10:13], v[160:163], v[220:223], v[10:13]
	v_mfma_f32_16x16x32_bf16 v[54:57], v[164:167], v[180:183], v[54:57]
	v_mfma_f32_16x16x32_bf16 v[50:53], v[172:175], v[180:183], v[50:53]
	v_mfma_f32_16x16x32_bf16 v[38:41], v[164:167], v[188:191], v[38:41]
	v_mfma_f32_16x16x32_bf16 v[34:37], v[172:175], v[188:191], v[34:37]
	v_mfma_f32_16x16x32_bf16 v[22:25], v[164:167], v[196:199], v[22:25]
	v_mfma_f32_16x16x32_bf16 v[18:21], v[172:175], v[196:199], v[18:21]
	v_mfma_f32_16x16x32_bf16 v[6:9], v[164:167], v[204:207], v[6:9]
	v_mfma_f32_16x16x32_bf16 v[2:5], v[172:175], v[204:207], v[2:5]
	v_mfma_f32_16x16x32_bf16 v[54:57], v[168:171], v[184:187], v[54:57]
	v_mfma_f32_16x16x32_bf16 v[50:53], v[176:179], v[184:187], v[50:53]
	v_mfma_f32_16x16x32_bf16 v[38:41], v[168:171], v[192:195], v[38:41]
	v_mfma_f32_16x16x32_bf16 v[34:37], v[176:179], v[192:195], v[34:37]
	v_mfma_f32_16x16x32_bf16 v[22:25], v[168:171], v[200:203], v[22:25]
	v_mfma_f32_16x16x32_bf16 v[18:21], v[176:179], v[200:203], v[18:21]
	v_mfma_f32_16x16x32_bf16 v[6:9], v[168:171], v[220:223], v[6:9]
	v_mfma_f32_16x16x32_bf16 v[2:5], v[176:179], v[220:223], v[2:5]
	s_barrier
	s_add_u32 s36, s36, 0x100
	s_addc_u32 s37, s37, 0
	v_add_u32_e32 v144, 0x100, v144
	v_add_u32_e32 v142, 0x100, v142
	s_cmp_ge_u32 s63, s56
	s_mov_b32 s31, s63
	s_cbranch_scc0 .LBB0_476
	s_and_b64 vcc, exec, s[6:7]
	s_cbranch_vccnz .LBB0_464
	v_mov_b32_e32 v2, 0
	s_mov_b32 s55, s61
	s_mov_b32 s50, s62
	s_mov_b64 s[26:27], s[34:35]
	s_mov_b64 s[28:29], s[8:9]
	s_mov_b32 s60, s30
	v_mov_b32_e32 v3, v2
	v_mov_b32_e32 v4, v2
	v_mov_b32_e32 v5, v2
	v_mov_b32_e32 v6, v2
	v_mov_b32_e32 v7, v2
	v_mov_b32_e32 v8, v2
	v_mov_b32_e32 v9, v2
	v_mov_b32_e32 v18, v2
	v_mov_b32_e32 v19, v2
	v_mov_b32_e32 v20, v2
	v_mov_b32_e32 v21, v2
	v_mov_b32_e32 v22, v2
	v_mov_b32_e32 v23, v2
	v_mov_b32_e32 v24, v2
	v_mov_b32_e32 v25, v2
	v_mov_b32_e32 v34, v2
	v_mov_b32_e32 v35, v2
	v_mov_b32_e32 v36, v2
	v_mov_b32_e32 v37, v2
	v_mov_b32_e32 v38, v2
	v_mov_b32_e32 v39, v2
	v_mov_b32_e32 v40, v2
	v_mov_b32_e32 v41, v2
	v_mov_b32_e32 v50, v2
	v_mov_b32_e32 v51, v2
	v_mov_b32_e32 v52, v2
	v_mov_b32_e32 v53, v2
	v_mov_b32_e32 v54, v2
	v_mov_b32_e32 v55, v2
	v_mov_b32_e32 v56, v2
	v_mov_b32_e32 v57, v2
	v_mov_b32_e32 v10, v2
	v_mov_b32_e32 v11, v2
	v_mov_b32_e32 v12, v2
	v_mov_b32_e32 v13, v2
	v_mov_b32_e32 v14, v2
	v_mov_b32_e32 v15, v2
	v_mov_b32_e32 v16, v2
	v_mov_b32_e32 v17, v2
	v_mov_b32_e32 v26, v2
	v_mov_b32_e32 v27, v2
	v_mov_b32_e32 v28, v2
	v_mov_b32_e32 v29, v2
	v_mov_b32_e32 v30, v2
	v_mov_b32_e32 v31, v2
	v_mov_b32_e32 v32, v2
	v_mov_b32_e32 v33, v2
	v_mov_b32_e32 v42, v2
	v_mov_b32_e32 v43, v2
	v_mov_b32_e32 v44, v2
	v_mov_b32_e32 v45, v2
	v_mov_b32_e32 v46, v2
	v_mov_b32_e32 v47, v2
	v_mov_b32_e32 v48, v2
	v_mov_b32_e32 v49, v2
	v_mov_b32_e32 v58, v2
	v_mov_b32_e32 v59, v2
	v_mov_b32_e32 v60, v2
	v_mov_b32_e32 v61, v2
	v_mov_b32_e32 v62, v2
	v_mov_b32_e32 v63, v2
	v_mov_b32_e32 v64, v2
	v_mov_b32_e32 v65, v2
	v_mov_b32_e32 v66, v2
	v_mov_b32_e32 v67, v2
	v_mov_b32_e32 v68, v2
	v_mov_b32_e32 v69, v2
	v_mov_b32_e32 v70, v2
	v_mov_b32_e32 v71, v2
	v_mov_b32_e32 v72, v2
	v_mov_b32_e32 v73, v2
	v_mov_b32_e32 v82, v2
	v_mov_b32_e32 v83, v2
	v_mov_b32_e32 v84, v2
	v_mov_b32_e32 v85, v2
	v_mov_b32_e32 v86, v2
	v_mov_b32_e32 v87, v2
	v_mov_b32_e32 v88, v2
	v_mov_b32_e32 v89, v2
	v_mov_b32_e32 v98, v2
	v_mov_b32_e32 v99, v2
	v_mov_b32_e32 v100, v2
	v_mov_b32_e32 v101, v2
	v_mov_b32_e32 v102, v2
	v_mov_b32_e32 v103, v2
	v_mov_b32_e32 v104, v2
	v_mov_b32_e32 v105, v2
	v_mov_b32_e32 v114, v2
	v_mov_b32_e32 v115, v2
	v_mov_b32_e32 v116, v2
	v_mov_b32_e32 v117, v2
	v_mov_b32_e32 v118, v2
	v_mov_b32_e32 v119, v2
	v_mov_b32_e32 v120, v2
	v_mov_b32_e32 v121, v2
	v_mov_b32_e32 v74, v2
	v_mov_b32_e32 v75, v2
	v_mov_b32_e32 v76, v2
	v_mov_b32_e32 v77, v2
	v_mov_b32_e32 v78, v2
	v_mov_b32_e32 v79, v2
	v_mov_b32_e32 v80, v2
	v_mov_b32_e32 v81, v2
	v_mov_b32_e32 v90, v2
	v_mov_b32_e32 v91, v2
	v_mov_b32_e32 v92, v2
	v_mov_b32_e32 v93, v2
	v_mov_b32_e32 v94, v2
	v_mov_b32_e32 v95, v2
	v_mov_b32_e32 v96, v2
	v_mov_b32_e32 v97, v2
	v_mov_b32_e32 v106, v2
	v_mov_b32_e32 v107, v2
	v_mov_b32_e32 v108, v2
	v_mov_b32_e32 v109, v2
	v_mov_b32_e32 v110, v2
	v_mov_b32_e32 v111, v2
	v_mov_b32_e32 v112, v2
	v_mov_b32_e32 v113, v2
	v_mov_b32_e32 v122, v2
	v_mov_b32_e32 v123, v2
	v_mov_b32_e32 v124, v2
	v_mov_b32_e32 v125, v2
	v_mov_b32_e32 v126, v2
	v_mov_b32_e32 v127, v2
	v_mov_b32_e32 v128, v2
	v_mov_b32_e32 v129, v2
	s_branch .LBB0_464

.LBB0_639:
	s_ashr_i32 s13, s12, 31
	s_lshl_b64 s[14:15], s[12:13], 19
	s_add_u32 s14, s80, s14
	s_addc_u32 s15, s81, s15
	s_and_b64 s[16:17], s[4:5], exec
	s_cselect_b32 s13, s15, s23
	s_cselect_b32 s19, s14, s22
	s_ashr_i32 s11, s10, 31
	s_lshl_b64 s[16:17], s[10:11], 19
	s_add_u32 s16, s26, s16
	s_addc_u32 s17, s27, s17
	s_and_b64 s[24:25], s[4:5], exec
	s_cselect_b32 s11, s17, s21
	s_cselect_b32 s41, s16, s20
	s_add_u32 s43, s20, 0x100
	s_addc_u32 s44, s21, 0
	s_add_u32 s20, s22, 0x40080
	s_addc_u32 s21, s23, 0
	s_mov_b32 s45, -2
	s_add_u32 s22, s20, 0xfffc0080
	s_addc_u32 s23, s21, -1
	s_add_i32 s46, 0, 0x10000
	s_cmp_eq_u32 s45, 12
	s_cselect_b32 s25, s13, s23
	s_cselect_b32 s24, s19, s22
	s_cselect_b32 s23, s11, s44
	s_cselect_b32 s22, s41, s43
	s_add_i32 s48, 0, 0x14000
	ds_read_b128 v[164:167], v159
	ds_read_b128 v[168:171], v159 offset:1024
	ds_read_b128 v[172:175], v159 offset:2048
	ds_read_b128 v[176:179], v159 offset:3072
	ds_read_b128 v[180:183], v159 offset:16384
	ds_read_b128 v[184:187], v159 offset:17408
	ds_read_b128 v[188:191], v159 offset:18432
	ds_read_b128 v[192:195], v159 offset:19456
	s_add_i32 m0, s30, 0xc000
	ds_read_b128 v[196:199], v162
	ds_read_b128 v[200:203], v162 offset:1024
	ds_read_b128 v[204:207], v162 offset:2048
	ds_read_b128 v[220:223], v162 offset:3072
	ds_read_b128 v[236:239], v162 offset:4096
	ds_read_b128 v[240:243], v162 offset:5120
	ds_read_b128 v[244:247], v162 offset:6144
	ds_read_b128 v[248:251], v162 offset:7168
	global_load_lds_dwordx4 v140, s[20:21]
	s_add_i32 m0, s30, 0xe000
	s_nop 0
	global_load_lds_dwordx4 v138, s[20:21]
	s_waitcnt vmcnt(8)
	s_waitcnt lgkmcnt(0)
	s_barrier
	v_mfma_f32_16x16x32_bf16 v[126:129], v[164:167], v[196:199], 0
	v_mfma_f32_16x16x32_bf16 v[122:125], v[172:175], v[196:199], 0
	v_mfma_f32_16x16x32_bf16 v[118:121], v[164:167], v[204:207], 0
	v_mfma_f32_16x16x32_bf16 v[114:117], v[172:175], v[204:207], 0
	v_mfma_f32_16x16x32_bf16 v[110:113], v[164:167], v[236:239], 0
	v_mfma_f32_16x16x32_bf16 v[106:109], v[172:175], v[236:239], 0
	v_mfma_f32_16x16x32_bf16 v[102:105], v[164:167], v[244:247], 0
	v_mfma_f32_16x16x32_bf16 v[98:101], v[172:175], v[244:247], 0
	v_mfma_f32_16x16x32_bf16 v[126:129], v[168:171], v[200:203], v[126:129]
	v_mfma_f32_16x16x32_bf16 v[122:125], v[176:179], v[200:203], v[122:125]
	v_mfma_f32_16x16x32_bf16 v[118:121], v[168:171], v[220:223], v[118:121]
	v_mfma_f32_16x16x32_bf16 v[114:117], v[176:179], v[220:223], v[114:117]
	v_mfma_f32_16x16x32_bf16 v[110:113], v[168:171], v[240:243], v[110:113]
	v_mfma_f32_16x16x32_bf16 v[106:109], v[176:179], v[240:243], v[106:109]
	v_mfma_f32_16x16x32_bf16 v[102:105], v[168:171], v[248:251], v[102:105]
	v_mfma_f32_16x16x32_bf16 v[98:101], v[176:179], v[248:251], v[98:101]
	v_mfma_f32_16x16x32_bf16 v[94:97], v[180:183], v[196:199], 0
	v_mfma_f32_16x16x32_bf16 v[90:93], v[188:191], v[196:199], 0
	v_mfma_f32_16x16x32_bf16 v[86:89], v[180:183], v[204:207], 0
	v_mfma_f32_16x16x32_bf16 v[82:85], v[188:191], v[204:207], 0
	v_mfma_f32_16x16x32_bf16 v[78:81], v[180:183], v[236:239], 0
	v_mfma_f32_16x16x32_bf16 v[74:77], v[188:191], v[236:239], 0
	v_mfma_f32_16x16x32_bf16 v[70:73], v[180:183], v[244:247], 0
	v_mfma_f32_16x16x32_bf16 v[66:69], v[188:191], v[244:247], 0
	v_mfma_f32_16x16x32_bf16 v[94:97], v[184:187], v[200:203], v[94:97]
	v_mfma_f32_16x16x32_bf16 v[90:93], v[192:195], v[200:203], v[90:93]
	v_mfma_f32_16x16x32_bf16 v[86:89], v[184:187], v[220:223], v[86:89]
	v_mfma_f32_16x16x32_bf16 v[82:85], v[192:195], v[220:223], v[82:85]
	v_mfma_f32_16x16x32_bf16 v[78:81], v[184:187], v[240:243], v[78:81]
	v_mfma_f32_16x16x32_bf16 v[74:77], v[192:195], v[240:243], v[74:77]
	v_mfma_f32_16x16x32_bf16 v[70:73], v[184:187], v[248:251], v[70:73]
	v_mfma_f32_16x16x32_bf16 v[66:69], v[192:195], v[248:251], v[66:69]
	s_barrier
	s_add_i32 s46, s46, s28
	s_mov_b32 m0, s46
	ds_read_b128 v[196:199], v162 offset:16384
	ds_read_b128 v[200:203], v162 offset:17408
	ds_read_b128 v[204:207], v162 offset:18432
	ds_read_b128 v[220:223], v162 offset:19456
	ds_read_b128 v[236:239], v162 offset:20480
	ds_read_b128 v[240:243], v162 offset:21504
	ds_read_b128 v[244:247], v162 offset:22528
	ds_read_b128 v[248:251], v162 offset:23552
	global_load_lds_dwordx4 v134, s[22:23]
	s_add_i32 m0, s46, 0x2000
	s_add_u32 s46, s22, 0x40000
	s_addc_u32 s47, s23, 0
	s_add_i32 s48, s48, s28
	global_load_lds_dwordx4 v130, s[22:23]
	s_mov_b32 m0, s48
	s_nop 0
	global_load_lds_dwordx4 v134, s[46:47]
	s_add_i32 m0, s48, 0x2000
	s_nop 0
	global_load_lds_dwordx4 v130, s[46:47]
	s_mov_b32 m0, s30
	s_nop 0
	global_load_lds_dwordx4 v136, s[24:25]
	s_mov_b32 m0, s31
	s_nop 0
	global_load_lds_dwordx4 v132, s[24:25]
	s_waitcnt vmcnt(8)
	s_waitcnt lgkmcnt(0)
	s_barrier
	v_mfma_f32_16x16x32_bf16 v[62:65], v[164:167], v[196:199], 0
	v_mfma_f32_16x16x32_bf16 v[58:61], v[172:175], v[196:199], 0
	v_mfma_f32_16x16x32_bf16 v[54:57], v[164:167], v[204:207], 0
	v_mfma_f32_16x16x32_bf16 v[50:53], v[172:175], v[204:207], 0
	v_mfma_f32_16x16x32_bf16 v[46:49], v[164:167], v[236:239], 0
	v_mfma_f32_16x16x32_bf16 v[42:45], v[172:175], v[236:239], 0
	v_mfma_f32_16x16x32_bf16 v[38:41], v[164:167], v[244:247], 0
	v_mfma_f32_16x16x32_bf16 v[34:37], v[172:175], v[244:247], 0
	v_mfma_f32_16x16x32_bf16 v[62:65], v[168:171], v[200:203], v[62:65]
	v_mfma_f32_16x16x32_bf16 v[58:61], v[176:179], v[200:203], v[58:61]
	v_mfma_f32_16x16x32_bf16 v[54:57], v[168:171], v[220:223], v[54:57]
	v_mfma_f32_16x16x32_bf16 v[50:53], v[176:179], v[220:223], v[50:53]
	v_mfma_f32_16x16x32_bf16 v[46:49], v[168:171], v[240:243], v[46:49]
	v_mfma_f32_16x16x32_bf16 v[42:45], v[176:179], v[240:243], v[42:45]
	v_mfma_f32_16x16x32_bf16 v[38:41], v[168:171], v[248:251], v[38:41]
	v_mfma_f32_16x16x32_bf16 v[34:37], v[176:179], v[248:251], v[34:37]
	v_mfma_f32_16x16x32_bf16 v[30:33], v[180:183], v[196:199], 0
	v_mfma_f32_16x16x32_bf16 v[26:29], v[188:191], v[196:199], 0
	v_mfma_f32_16x16x32_bf16 v[22:25], v[180:183], v[204:207], 0
	v_mfma_f32_16x16x32_bf16 v[18:21], v[188:191], v[204:207], 0
	v_mfma_f32_16x16x32_bf16 v[14:17], v[180:183], v[236:239], 0
	v_mfma_f32_16x16x32_bf16 v[10:13], v[188:191], v[236:239], 0
	v_mfma_f32_16x16x32_bf16 v[6:9], v[180:183], v[244:247], 0
	v_mfma_f32_16x16x32_bf16 v[2:5], v[188:191], v[244:247], 0
	v_mfma_f32_16x16x32_bf16 v[30:33], v[184:187], v[200:203], v[30:33]
	v_mfma_f32_16x16x32_bf16 v[26:29], v[192:195], v[200:203], v[26:29]
	v_mfma_f32_16x16x32_bf16 v[22:25], v[184:187], v[220:223], v[22:25]
	v_mfma_f32_16x16x32_bf16 v[18:21], v[192:195], v[220:223], v[18:21]
	v_mfma_f32_16x16x32_bf16 v[14:17], v[184:187], v[240:243], v[14:17]
	v_mfma_f32_16x16x32_bf16 v[10:13], v[192:195], v[240:243], v[10:13]
	v_mfma_f32_16x16x32_bf16 v[6:9], v[184:187], v[248:251], v[6:9]
	v_mfma_f32_16x16x32_bf16 v[2:5], v[192:195], v[248:251], v[2:5]
	s_barrier
	s_add_i32 s46, 0, 0x18000
	s_add_i32 s47, 0, 0x1c000
	ds_read_b128 v[164:167], v159 offset:32768
	ds_read_b128 v[168:171], v159 offset:33792
	ds_read_b128 v[172:175], v159 offset:34816
	ds_read_b128 v[176:179], v159 offset:35840
	ds_read_b128 v[180:183], v159 offset:49152
	ds_read_b128 v[184:187], v159 offset:50176
	ds_read_b128 v[188:191], v159 offset:51200
	ds_read_b128 v[192:195], v159 offset:52224
	s_add_u32 s24, s24, 0x40000
	s_addc_u32 s25, s25, 0
	s_mov_b32 m0, s34
	ds_read_b128 v[196:199], v162 offset:32768
	ds_read_b128 v[200:203], v162 offset:33792
	ds_read_b128 v[204:207], v162 offset:34816
	ds_read_b128 v[220:223], v162 offset:35840
	ds_read_b128 v[236:239], v162 offset:36864
	ds_read_b128 v[240:243], v162 offset:37888
	ds_read_b128 v[244:247], v162 offset:38912
	ds_read_b128 v[248:251], v162 offset:39936
	global_load_lds_dwordx4 v136, s[24:25]
	s_mov_b32 m0, s35
	s_nop 0
	global_load_lds_dwordx4 v132, s[24:25]
	s_waitcnt vmcnt(8)
	s_waitcnt lgkmcnt(0)
	s_barrier
	v_mfma_f32_16x16x32_bf16 v[126:129], v[164:167], v[196:199], v[126:129]
	v_mfma_f32_16x16x32_bf16 v[122:125], v[172:175], v[196:199], v[122:125]
	v_mfma_f32_16x16x32_bf16 v[118:121], v[164:167], v[204:207], v[118:121]
	v_mfma_f32_16x16x32_bf16 v[114:117], v[172:175], v[204:207], v[114:117]
	v_mfma_f32_16x16x32_bf16 v[110:113], v[164:167], v[236:239], v[110:113]
	v_mfma_f32_16x16x32_bf16 v[106:109], v[172:175], v[236:239], v[106:109]
	v_mfma_f32_16x16x32_bf16 v[102:105], v[164:167], v[244:247], v[102:105]
	v_mfma_f32_16x16x32_bf16 v[98:101], v[172:175], v[244:247], v[98:101]
	v_mfma_f32_16x16x32_bf16 v[126:129], v[168:171], v[200:203], v[126:129]
	v_mfma_f32_16x16x32_bf16 v[122:125], v[176:179], v[200:203], v[122:125]
	v_mfma_f32_16x16x32_bf16 v[118:121], v[168:171], v[220:223], v[118:121]
	v_mfma_f32_16x16x32_bf16 v[114:117], v[176:179], v[220:223], v[114:117]
	v_mfma_f32_16x16x32_bf16 v[110:113], v[168:171], v[240:243], v[110:113]
	v_mfma_f32_16x16x32_bf16 v[106:109], v[176:179], v[240:243], v[106:109]
	v_mfma_f32_16x16x32_bf16 v[102:105], v[168:171], v[248:251], v[102:105]
	v_mfma_f32_16x16x32_bf16 v[98:101], v[176:179], v[248:251], v[98:101]
	v_mfma_f32_16x16x32_bf16 v[94:97], v[180:183], v[196:199], v[94:97]
	v_mfma_f32_16x16x32_bf16 v[90:93], v[188:191], v[196:199], v[90:93]
	v_mfma_f32_16x16x32_bf16 v[86:89], v[180:183], v[204:207], v[86:89]
	v_mfma_f32_16x16x32_bf16 v[82:85], v[188:191], v[204:207], v[82:85]
	v_mfma_f32_16x16x32_bf16 v[78:81], v[180:183], v[236:239], v[78:81]
	v_mfma_f32_16x16x32_bf16 v[74:77], v[188:191], v[236:239], v[74:77]
	v_mfma_f32_16x16x32_bf16 v[70:73], v[180:183], v[244:247], v[70:73]
	v_mfma_f32_16x16x32_bf16 v[66:69], v[188:191], v[244:247], v[66:69]
	v_mfma_f32_16x16x32_bf16 v[94:97], v[184:187], v[200:203], v[94:97]
	v_mfma_f32_16x16x32_bf16 v[90:93], v[192:195], v[200:203], v[90:93]
	v_mfma_f32_16x16x32_bf16 v[86:89], v[184:187], v[220:223], v[86:89]
	v_mfma_f32_16x16x32_bf16 v[82:85], v[192:195], v[220:223], v[82:85]
	v_mfma_f32_16x16x32_bf16 v[78:81], v[184:187], v[240:243], v[78:81]
	v_mfma_f32_16x16x32_bf16 v[74:77], v[192:195], v[240:243], v[74:77]
	v_mfma_f32_16x16x32_bf16 v[70:73], v[184:187], v[248:251], v[70:73]
	v_mfma_f32_16x16x32_bf16 v[66:69], v[192:195], v[248:251], v[66:69]
	s_barrier
	s_add_u32 s100, s24, 0xfffc0080
	s_addc_u32 s101, s25, -1
	s_add_u32 s22, s22, 0x80
	s_addc_u32 s23, s23, 0
	s_add_i32 s24, s46, s28
	s_mov_b32 m0, s24
	ds_read_b128 v[196:199], v162 offset:49152
	ds_read_b128 v[200:203], v162 offset:50176
	ds_read_b128 v[204:207], v162 offset:51200
	ds_read_b128 v[220:223], v162 offset:52224
	ds_read_b128 v[236:239], v162 offset:53248
	ds_read_b128 v[240:243], v162 offset:54272
	ds_read_b128 v[244:247], v162 offset:55296
	ds_read_b128 v[248:251], v162 offset:56320
	global_load_lds_dwordx4 v134, s[22:23]
	s_add_i32 m0, s24, 0x2000
	s_add_i32 s24, s47, s28
	global_load_lds_dwordx4 v130, s[22:23]
	s_add_u32 s22, s22, 0x40000
	s_addc_u32 s23, s23, 0
	s_mov_b32 m0, s24
	s_nop 0
	global_load_lds_dwordx4 v134, s[22:23]
	s_add_i32 m0, s24, 0x2000
	s_nop 0
	global_load_lds_dwordx4 v130, s[22:23]
	s_mov_b32 m0, s36
	s_nop 0
	global_load_lds_dwordx4 v136, s[100:101]
	s_mov_b32 m0, s37
	s_nop 0
	global_load_lds_dwordx4 v132, s[100:101]
	s_waitcnt vmcnt(8)
	s_waitcnt lgkmcnt(0)
	s_barrier
	v_mfma_f32_16x16x32_bf16 v[62:65], v[164:167], v[196:199], v[62:65]
	v_mfma_f32_16x16x32_bf16 v[58:61], v[172:175], v[196:199], v[58:61]
	v_mfma_f32_16x16x32_bf16 v[54:57], v[164:167], v[204:207], v[54:57]
	v_mfma_f32_16x16x32_bf16 v[50:53], v[172:175], v[204:207], v[50:53]
	v_mfma_f32_16x16x32_bf16 v[46:49], v[164:167], v[236:239], v[46:49]
	v_mfma_f32_16x16x32_bf16 v[42:45], v[172:175], v[236:239], v[42:45]
	v_mfma_f32_16x16x32_bf16 v[38:41], v[164:167], v[244:247], v[38:41]
	v_mfma_f32_16x16x32_bf16 v[34:37], v[172:175], v[244:247], v[34:37]
	v_mfma_f32_16x16x32_bf16 v[62:65], v[168:171], v[200:203], v[62:65]
	v_mfma_f32_16x16x32_bf16 v[58:61], v[176:179], v[200:203], v[58:61]
	v_mfma_f32_16x16x32_bf16 v[54:57], v[168:171], v[220:223], v[54:57]
	v_mfma_f32_16x16x32_bf16 v[50:53], v[176:179], v[220:223], v[50:53]
	v_mfma_f32_16x16x32_bf16 v[46:49], v[168:171], v[240:243], v[46:49]
	v_mfma_f32_16x16x32_bf16 v[42:45], v[176:179], v[240:243], v[42:45]
	v_mfma_f32_16x16x32_bf16 v[38:41], v[168:171], v[248:251], v[38:41]
	v_mfma_f32_16x16x32_bf16 v[34:37], v[176:179], v[248:251], v[34:37]
	v_mfma_f32_16x16x32_bf16 v[30:33], v[180:183], v[196:199], v[30:33]
	v_mfma_f32_16x16x32_bf16 v[26:29], v[188:191], v[196:199], v[26:29]
	v_mfma_f32_16x16x32_bf16 v[22:25], v[180:183], v[204:207], v[22:25]
	v_mfma_f32_16x16x32_bf16 v[18:21], v[188:191], v[204:207], v[18:21]
	v_mfma_f32_16x16x32_bf16 v[14:17], v[180:183], v[236:239], v[14:17]
	v_mfma_f32_16x16x32_bf16 v[10:13], v[188:191], v[236:239], v[10:13]
	v_mfma_f32_16x16x32_bf16 v[6:9], v[180:183], v[244:247], v[6:9]
	v_mfma_f32_16x16x32_bf16 v[2:5], v[188:191], v[244:247], v[2:5]
	v_mfma_f32_16x16x32_bf16 v[30:33], v[184:187], v[200:203], v[30:33]
	v_mfma_f32_16x16x32_bf16 v[26:29], v[192:195], v[200:203], v[26:29]
	v_mfma_f32_16x16x32_bf16 v[22:25], v[184:187], v[220:223], v[22:25]
	v_mfma_f32_16x16x32_bf16 v[18:21], v[192:195], v[220:223], v[18:21]
	v_mfma_f32_16x16x32_bf16 v[14:17], v[184:187], v[240:243], v[14:17]
	v_mfma_f32_16x16x32_bf16 v[10:13], v[192:195], v[240:243], v[10:13]
	v_mfma_f32_16x16x32_bf16 v[6:9], v[184:187], v[248:251], v[6:9]
	v_mfma_f32_16x16x32_bf16 v[2:5], v[192:195], v[248:251], v[2:5]
	s_barrier
	s_add_i32 s45, s45, 2
	s_add_u32 s43, s43, 0x100
	s_addc_u32 s44, s44, 0
	s_add_u32 s20, s20, 0x100
	s_addc_u32 s21, s21, 0
	s_cmp_gt_u32 s45, 13
.LBB0_640:
	s_add_u32 s22, s20, 0xfffc0080
	s_addc_u32 s23, s21, -1
	s_add_i32 s46, 0, 0x10000
	s_cmp_eq_u32 s45, 12
	s_cselect_b32 s25, s13, s23
	s_cselect_b32 s24, s19, s22
	s_cselect_b32 s23, s11, s44
	s_cselect_b32 s22, s41, s43
	s_add_i32 s48, 0, 0x14000
	ds_read_b128 v[164:167], v159
	ds_read_b128 v[168:171], v159 offset:1024
	ds_read_b128 v[172:175], v159 offset:2048
	ds_read_b128 v[176:179], v159 offset:3072
	ds_read_b128 v[180:183], v159 offset:16384
	ds_read_b128 v[184:187], v159 offset:17408
	ds_read_b128 v[188:191], v159 offset:18432
	ds_read_b128 v[192:195], v159 offset:19456
	s_add_i32 m0, s30, 0xc000
	ds_read_b128 v[196:199], v162
	ds_read_b128 v[200:203], v162 offset:1024
	ds_read_b128 v[204:207], v162 offset:2048
	ds_read_b128 v[220:223], v162 offset:3072
	ds_read_b128 v[236:239], v162 offset:4096
	ds_read_b128 v[240:243], v162 offset:5120
	ds_read_b128 v[244:247], v162 offset:6144
	global_load_lds_dwordx4 v140, s[20:21]
	s_add_i32 m0, s30, 0xe000
	ds_read_b128 v[248:251], v162 offset:7168
	global_load_lds_dwordx4 v138, s[20:21]
	s_waitcnt vmcnt(8)
	s_waitcnt lgkmcnt(0)
	s_barrier
	v_mfma_f32_16x16x32_bf16 v[126:129], v[164:167], v[196:199], v[126:129]
	v_mfma_f32_16x16x32_bf16 v[122:125], v[172:175], v[196:199], v[122:125]
	v_mfma_f32_16x16x32_bf16 v[118:121], v[164:167], v[204:207], v[118:121]
	v_mfma_f32_16x16x32_bf16 v[114:117], v[172:175], v[204:207], v[114:117]
	v_mfma_f32_16x16x32_bf16 v[110:113], v[164:167], v[236:239], v[110:113]
	v_mfma_f32_16x16x32_bf16 v[106:109], v[172:175], v[236:239], v[106:109]
	v_mfma_f32_16x16x32_bf16 v[102:105], v[164:167], v[244:247], v[102:105]
	v_mfma_f32_16x16x32_bf16 v[98:101], v[172:175], v[244:247], v[98:101]
	v_mfma_f32_16x16x32_bf16 v[126:129], v[168:171], v[200:203], v[126:129]
	v_mfma_f32_16x16x32_bf16 v[122:125], v[176:179], v[200:203], v[122:125]
	v_mfma_f32_16x16x32_bf16 v[118:121], v[168:171], v[220:223], v[118:121]
	v_mfma_f32_16x16x32_bf16 v[114:117], v[176:179], v[220:223], v[114:117]
	v_mfma_f32_16x16x32_bf16 v[110:113], v[168:171], v[240:243], v[110:113]
	v_mfma_f32_16x16x32_bf16 v[106:109], v[176:179], v[240:243], v[106:109]
	v_mfma_f32_16x16x32_bf16 v[102:105], v[168:171], v[248:251], v[102:105]
	v_mfma_f32_16x16x32_bf16 v[98:101], v[176:179], v[248:251], v[98:101]
	v_mfma_f32_16x16x32_bf16 v[94:97], v[180:183], v[196:199], v[94:97]
	v_mfma_f32_16x16x32_bf16 v[90:93], v[188:191], v[196:199], v[90:93]
	v_mfma_f32_16x16x32_bf16 v[86:89], v[180:183], v[204:207], v[86:89]
	v_mfma_f32_16x16x32_bf16 v[82:85], v[188:191], v[204:207], v[82:85]
	v_mfma_f32_16x16x32_bf16 v[78:81], v[180:183], v[236:239], v[78:81]
	v_mfma_f32_16x16x32_bf16 v[74:77], v[188:191], v[236:239], v[74:77]
	v_mfma_f32_16x16x32_bf16 v[70:73], v[180:183], v[244:247], v[70:73]
	v_mfma_f32_16x16x32_bf16 v[66:69], v[188:191], v[244:247], v[66:69]
	v_mfma_f32_16x16x32_bf16 v[94:97], v[184:187], v[200:203], v[94:97]
	v_mfma_f32_16x16x32_bf16 v[90:93], v[192:195], v[200:203], v[90:93]
	v_mfma_f32_16x16x32_bf16 v[86:89], v[184:187], v[220:223], v[86:89]
	v_mfma_f32_16x16x32_bf16 v[82:85], v[192:195], v[220:223], v[82:85]
	v_mfma_f32_16x16x32_bf16 v[78:81], v[184:187], v[240:243], v[78:81]
	v_mfma_f32_16x16x32_bf16 v[74:77], v[192:195], v[240:243], v[74:77]
	v_mfma_f32_16x16x32_bf16 v[70:73], v[184:187], v[248:251], v[70:73]
	v_mfma_f32_16x16x32_bf16 v[66:69], v[192:195], v[248:251], v[66:69]
	s_barrier
	s_add_i32 s46, s46, s28
	s_mov_b32 m0, s46
	ds_read_b128 v[196:199], v162 offset:16384
	ds_read_b128 v[200:203], v162 offset:17408
	ds_read_b128 v[204:207], v162 offset:18432
	ds_read_b128 v[220:223], v162 offset:19456
	global_load_lds_dwordx4 v134, s[22:23]
	s_add_i32 m0, s46, 0x2000
	s_add_u32 s46, s22, 0x40000
	s_addc_u32 s47, s23, 0
	s_add_i32 s48, s48, s28
	global_load_lds_dwordx4 v130, s[22:23]
	s_mov_b32 m0, s48
	ds_read_b128 v[236:239], v162 offset:20480
	global_load_lds_dwordx4 v134, s[46:47]
	s_add_i32 m0, s48, 0x2000
	ds_read_b128 v[240:243], v162 offset:21504
	global_load_lds_dwordx4 v130, s[46:47]
	s_mov_b32 m0, s30
	ds_read_b128 v[244:247], v162 offset:22528
	global_load_lds_dwordx4 v136, s[24:25]
	s_mov_b32 m0, s31
	ds_read_b128 v[248:251], v162 offset:23552
	global_load_lds_dwordx4 v132, s[24:25]
	s_waitcnt vmcnt(8)
	s_waitcnt lgkmcnt(0)
	s_barrier
	v_mfma_f32_16x16x32_bf16 v[62:65], v[164:167], v[196:199], v[62:65]
	v_mfma_f32_16x16x32_bf16 v[58:61], v[172:175], v[196:199], v[58:61]
	v_mfma_f32_16x16x32_bf16 v[54:57], v[164:167], v[204:207], v[54:57]
	v_mfma_f32_16x16x32_bf16 v[50:53], v[172:175], v[204:207], v[50:53]
	v_mfma_f32_16x16x32_bf16 v[46:49], v[164:167], v[236:239], v[46:49]
	v_mfma_f32_16x16x32_bf16 v[42:45], v[172:175], v[236:239], v[42:45]
	v_mfma_f32_16x16x32_bf16 v[38:41], v[164:167], v[244:247], v[38:41]
	v_mfma_f32_16x16x32_bf16 v[34:37], v[172:175], v[244:247], v[34:37]
	v_mfma_f32_16x16x32_bf16 v[62:65], v[168:171], v[200:203], v[62:65]
	v_mfma_f32_16x16x32_bf16 v[58:61], v[176:179], v[200:203], v[58:61]
	v_mfma_f32_16x16x32_bf16 v[54:57], v[168:171], v[220:223], v[54:57]
	v_mfma_f32_16x16x32_bf16 v[50:53], v[176:179], v[220:223], v[50:53]
	v_mfma_f32_16x16x32_bf16 v[46:49], v[168:171], v[240:243], v[46:49]
	v_mfma_f32_16x16x32_bf16 v[42:45], v[176:179], v[240:243], v[42:45]
	v_mfma_f32_16x16x32_bf16 v[38:41], v[168:171], v[248:251], v[38:41]
	v_mfma_f32_16x16x32_bf16 v[34:37], v[176:179], v[248:251], v[34:37]
	v_mfma_f32_16x16x32_bf16 v[30:33], v[180:183], v[196:199], v[30:33]
	v_mfma_f32_16x16x32_bf16 v[26:29], v[188:191], v[196:199], v[26:29]
	v_mfma_f32_16x16x32_bf16 v[22:25], v[180:183], v[204:207], v[22:25]
	v_mfma_f32_16x16x32_bf16 v[18:21], v[188:191], v[204:207], v[18:21]
	v_mfma_f32_16x16x32_bf16 v[14:17], v[180:183], v[236:239], v[14:17]
	v_mfma_f32_16x16x32_bf16 v[10:13], v[188:191], v[236:239], v[10:13]
	v_mfma_f32_16x16x32_bf16 v[6:9], v[180:183], v[244:247], v[6:9]
	v_mfma_f32_16x16x32_bf16 v[2:5], v[188:191], v[244:247], v[2:5]
	v_mfma_f32_16x16x32_bf16 v[30:33], v[184:187], v[200:203], v[30:33]
	v_mfma_f32_16x16x32_bf16 v[26:29], v[192:195], v[200:203], v[26:29]
	v_mfma_f32_16x16x32_bf16 v[22:25], v[184:187], v[220:223], v[22:25]
	v_mfma_f32_16x16x32_bf16 v[18:21], v[192:195], v[220:223], v[18:21]
	v_mfma_f32_16x16x32_bf16 v[14:17], v[184:187], v[240:243], v[14:17]
	v_mfma_f32_16x16x32_bf16 v[10:13], v[192:195], v[240:243], v[10:13]
	v_mfma_f32_16x16x32_bf16 v[6:9], v[184:187], v[248:251], v[6:9]
	v_mfma_f32_16x16x32_bf16 v[2:5], v[192:195], v[248:251], v[2:5]
	s_barrier
	s_add_i32 s46, 0, 0x18000
	s_add_i32 s47, 0, 0x1c000
	ds_read_b128 v[164:167], v159 offset:32768
	ds_read_b128 v[168:171], v159 offset:33792
	ds_read_b128 v[172:175], v159 offset:34816
	ds_read_b128 v[176:179], v159 offset:35840
	ds_read_b128 v[180:183], v159 offset:49152
	ds_read_b128 v[184:187], v159 offset:50176
	ds_read_b128 v[188:191], v159 offset:51200
	ds_read_b128 v[192:195], v159 offset:52224
	s_add_u32 s24, s24, 0x40000
	s_addc_u32 s25, s25, 0
	s_mov_b32 m0, s34
	ds_read_b128 v[196:199], v162 offset:32768
	ds_read_b128 v[200:203], v162 offset:33792
	ds_read_b128 v[204:207], v162 offset:34816
	ds_read_b128 v[220:223], v162 offset:35840
	ds_read_b128 v[236:239], v162 offset:36864
	ds_read_b128 v[240:243], v162 offset:37888
	ds_read_b128 v[244:247], v162 offset:38912
	global_load_lds_dwordx4 v136, s[24:25]
	s_mov_b32 m0, s35
	ds_read_b128 v[248:251], v162 offset:39936
	global_load_lds_dwordx4 v132, s[24:25]
	s_waitcnt vmcnt(8)
	s_waitcnt lgkmcnt(0)
	s_barrier
	v_mfma_f32_16x16x32_bf16 v[126:129], v[164:167], v[196:199], v[126:129]
	v_mfma_f32_16x16x32_bf16 v[122:125], v[172:175], v[196:199], v[122:125]
	v_mfma_f32_16x16x32_bf16 v[118:121], v[164:167], v[204:207], v[118:121]
	v_mfma_f32_16x16x32_bf16 v[114:117], v[172:175], v[204:207], v[114:117]
	v_mfma_f32_16x16x32_bf16 v[110:113], v[164:167], v[236:239], v[110:113]
	v_mfma_f32_16x16x32_bf16 v[106:109], v[172:175], v[236:239], v[106:109]
	v_mfma_f32_16x16x32_bf16 v[102:105], v[164:167], v[244:247], v[102:105]
	v_mfma_f32_16x16x32_bf16 v[98:101], v[172:175], v[244:247], v[98:101]
	v_mfma_f32_16x16x32_bf16 v[126:129], v[168:171], v[200:203], v[126:129]
	v_mfma_f32_16x16x32_bf16 v[122:125], v[176:179], v[200:203], v[122:125]
	v_mfma_f32_16x16x32_bf16 v[118:121], v[168:171], v[220:223], v[118:121]
	v_mfma_f32_16x16x32_bf16 v[114:117], v[176:179], v[220:223], v[114:117]
	v_mfma_f32_16x16x32_bf16 v[110:113], v[168:171], v[240:243], v[110:113]
	v_mfma_f32_16x16x32_bf16 v[106:109], v[176:179], v[240:243], v[106:109]
	v_mfma_f32_16x16x32_bf16 v[102:105], v[168:171], v[248:251], v[102:105]
	v_mfma_f32_16x16x32_bf16 v[98:101], v[176:179], v[248:251], v[98:101]
	v_mfma_f32_16x16x32_bf16 v[94:97], v[180:183], v[196:199], v[94:97]
	v_mfma_f32_16x16x32_bf16 v[90:93], v[188:191], v[196:199], v[90:93]
	v_mfma_f32_16x16x32_bf16 v[86:89], v[180:183], v[204:207], v[86:89]
	v_mfma_f32_16x16x32_bf16 v[82:85], v[188:191], v[204:207], v[82:85]
	v_mfma_f32_16x16x32_bf16 v[78:81], v[180:183], v[236:239], v[78:81]
	v_mfma_f32_16x16x32_bf16 v[74:77], v[188:191], v[236:239], v[74:77]
	v_mfma_f32_16x16x32_bf16 v[70:73], v[180:183], v[244:247], v[70:73]
	v_mfma_f32_16x16x32_bf16 v[66:69], v[188:191], v[244:247], v[66:69]
	v_mfma_f32_16x16x32_bf16 v[94:97], v[184:187], v[200:203], v[94:97]
	v_mfma_f32_16x16x32_bf16 v[90:93], v[192:195], v[200:203], v[90:93]
	v_mfma_f32_16x16x32_bf16 v[86:89], v[184:187], v[220:223], v[86:89]
	v_mfma_f32_16x16x32_bf16 v[82:85], v[192:195], v[220:223], v[82:85]
	v_mfma_f32_16x16x32_bf16 v[78:81], v[184:187], v[240:243], v[78:81]
	v_mfma_f32_16x16x32_bf16 v[74:77], v[192:195], v[240:243], v[74:77]
	v_mfma_f32_16x16x32_bf16 v[70:73], v[184:187], v[248:251], v[70:73]
	v_mfma_f32_16x16x32_bf16 v[66:69], v[192:195], v[248:251], v[66:69]
	s_barrier
	s_add_u32 s100, s24, 0xfffc0080
	s_addc_u32 s101, s25, -1
	s_add_u32 s22, s22, 0x80
	s_addc_u32 s23, s23, 0
	s_add_i32 s24, s46, s28
	s_mov_b32 m0, s24
	ds_read_b128 v[196:199], v162 offset:49152
	ds_read_b128 v[200:203], v162 offset:50176
	ds_read_b128 v[204:207], v162 offset:51200
	ds_read_b128 v[220:223], v162 offset:52224
	global_load_lds_dwordx4 v134, s[22:23]
	s_add_i32 m0, s24, 0x2000
	s_add_i32 s24, s47, s28
	global_load_lds_dwordx4 v130, s[22:23]
	s_add_u32 s22, s22, 0x40000
	s_addc_u32 s23, s23, 0
	s_mov_b32 m0, s24
	ds_read_b128 v[236:239], v162 offset:53248
	global_load_lds_dwordx4 v134, s[22:23]
	s_add_i32 m0, s24, 0x2000
	ds_read_b128 v[240:243], v162 offset:54272
	global_load_lds_dwordx4 v130, s[22:23]
	s_mov_b32 m0, s36
	ds_read_b128 v[244:247], v162 offset:55296
	global_load_lds_dwordx4 v136, s[100:101]
	s_mov_b32 m0, s37
	ds_read_b128 v[248:251], v162 offset:56320
	global_load_lds_dwordx4 v132, s[100:101]
	s_waitcnt vmcnt(8)
	s_waitcnt lgkmcnt(0)
	s_barrier
	v_mfma_f32_16x16x32_bf16 v[62:65], v[164:167], v[196:199], v[62:65]
	v_mfma_f32_16x16x32_bf16 v[58:61], v[172:175], v[196:199], v[58:61]
	v_mfma_f32_16x16x32_bf16 v[54:57], v[164:167], v[204:207], v[54:57]
	v_mfma_f32_16x16x32_bf16 v[50:53], v[172:175], v[204:207], v[50:53]
	v_mfma_f32_16x16x32_bf16 v[46:49], v[164:167], v[236:239], v[46:49]
	v_mfma_f32_16x16x32_bf16 v[42:45], v[172:175], v[236:239], v[42:45]
	v_mfma_f32_16x16x32_bf16 v[38:41], v[164:167], v[244:247], v[38:41]
	v_mfma_f32_16x16x32_bf16 v[34:37], v[172:175], v[244:247], v[34:37]
	v_mfma_f32_16x16x32_bf16 v[62:65], v[168:171], v[200:203], v[62:65]
	v_mfma_f32_16x16x32_bf16 v[58:61], v[176:179], v[200:203], v[58:61]
	v_mfma_f32_16x16x32_bf16 v[54:57], v[168:171], v[220:223], v[54:57]
	v_mfma_f32_16x16x32_bf16 v[50:53], v[176:179], v[220:223], v[50:53]
	v_mfma_f32_16x16x32_bf16 v[46:49], v[168:171], v[240:243], v[46:49]
	v_mfma_f32_16x16x32_bf16 v[42:45], v[176:179], v[240:243], v[42:45]
	v_mfma_f32_16x16x32_bf16 v[38:41], v[168:171], v[248:251], v[38:41]
	v_mfma_f32_16x16x32_bf16 v[34:37], v[176:179], v[248:251], v[34:37]
	v_mfma_f32_16x16x32_bf16 v[30:33], v[180:183], v[196:199], v[30:33]
	v_mfma_f32_16x16x32_bf16 v[26:29], v[188:191], v[196:199], v[26:29]
	v_mfma_f32_16x16x32_bf16 v[22:25], v[180:183], v[204:207], v[22:25]
	v_mfma_f32_16x16x32_bf16 v[18:21], v[188:191], v[204:207], v[18:21]
	v_mfma_f32_16x16x32_bf16 v[14:17], v[180:183], v[236:239], v[14:17]
	v_mfma_f32_16x16x32_bf16 v[10:13], v[188:191], v[236:239], v[10:13]
	v_mfma_f32_16x16x32_bf16 v[6:9], v[180:183], v[244:247], v[6:9]
	v_mfma_f32_16x16x32_bf16 v[2:5], v[188:191], v[244:247], v[2:5]
	v_mfma_f32_16x16x32_bf16 v[30:33], v[184:187], v[200:203], v[30:33]
	v_mfma_f32_16x16x32_bf16 v[26:29], v[192:195], v[200:203], v[26:29]
	v_mfma_f32_16x16x32_bf16 v[22:25], v[184:187], v[220:223], v[22:25]
	v_mfma_f32_16x16x32_bf16 v[18:21], v[192:195], v[220:223], v[18:21]
	v_mfma_f32_16x16x32_bf16 v[14:17], v[184:187], v[240:243], v[14:17]
	v_mfma_f32_16x16x32_bf16 v[10:13], v[192:195], v[240:243], v[10:13]
	v_mfma_f32_16x16x32_bf16 v[6:9], v[184:187], v[248:251], v[6:9]
	v_mfma_f32_16x16x32_bf16 v[2:5], v[192:195], v[248:251], v[2:5]
	s_barrier
	s_add_i32 s45, s45, 2
	s_add_u32 s43, s43, 0x100
	s_addc_u32 s44, s44, 0
	s_add_u32 s20, s20, 0x100
	s_addc_u32 s21, s21, 0
	s_cmp_gt_u32 s45, 13
	s_cbranch_scc0 .LBB0_640
	s_and_b64 vcc, exec, s[8:9]
	s_cbranch_vccz .LBB0_643
	s_barrier
